# half-tile (128x64) k-loops: prefetch loads issued first in each half, LDS stores after the MFMAs (longer load->store distance)
# baseline (speedup 1.0000x reference)
.LBB0_119:
	s_add_i32 s2, s3, 2
	s_add_i32 s3, s3, 4
	s_min_u32 s3, s3, 15
	s_lshl_b32 s92, s3, 7
	v_lshl_add_u64 v[44:45], v[80:81], 0, s[92:93]
	v_add_co_u32_e32 v46, vcc, s11, v44
	s_nop 1
	v_addc_co_u32_e32 v47, vcc, 0, v45, vcc
	global_load_dwordx4 v[72:75], v[44:45], off
	global_load_dwordx4 v[64:67], v[46:47], off
	v_add_co_u32_e32 v46, vcc, s33, v44
	s_nop 1
	v_addc_co_u32_e32 v47, vcc, 0, v45, vcc
	v_add_co_u32_e32 v44, vcc, s59, v44
	global_load_dwordx4 v[60:63], v[46:47], off
	s_nop 1
	v_addc_co_u32_e32 v45, vcc, 0, v45, vcc
	global_load_dwordx4 v[56:59], v[44:45], off
	v_lshl_add_u64 v[44:45], v[82:83], 0, s[92:93]
	global_load_dwordx4 v[48:51], v[44:45], off
	v_add_co_u32_e32 v44, vcc, s11, v44
	s_nop 1
	v_addc_co_u32_e32 v45, vcc, 0, v45, vcc
	global_load_dwordx4 v[44:47], v[44:45], off
	v_add_u32_e32 v127, v89, v90
	ds_read_b128 v[100:103], v127 offset:16384
	ds_read_b128 v[106:109], v127 offset:18432
	ds_read_b128 v[110:113], v127 offset:20480
	ds_read_b128 v[114:117], v127 offset:22528
	v_add_u32_e32 v126, v88, v90
	ds_read_b128 v[92:95], v126
	ds_read_b128 v[96:99], v126 offset:2048
	v_add_u32_e32 v128, v88, v91
	v_add_u32_e32 v130, v89, v91
	ds_read_b128 v[118:121], v130 offset:18432
	ds_read_b128 v[122:125], v130 offset:20480
	ds_read_b128 v[132:135], v130 offset:22528
	s_waitcnt lgkmcnt(4)
	v_mfma_f32_16x16x32_bf16 v[76:79], v[100:103], v[92:95], v[76:79]
	v_mfma_f32_16x16x32_bf16 v[68:71], v[106:109], v[92:95], v[68:71]
	v_mfma_f32_16x16x32_bf16 v[52:55], v[110:113], v[92:95], v[52:55]
	v_mfma_f32_16x16x32_bf16 v[40:43], v[114:117], v[92:95], v[40:43]
	s_waitcnt lgkmcnt(3)
	v_mfma_f32_16x16x32_bf16 v[92:95], v[100:103], v[96:99], v[36:39]
	s_nop 2
	ds_read_b128 v[36:39], v128
	v_mfma_f32_16x16x32_bf16 v[100:103], v[106:109], v[96:99], v[8:11]
	v_mfma_f32_16x16x32_bf16 v[106:109], v[110:113], v[96:99], v[4:7]
	ds_read_b128 v[110:113], v128 offset:2048
	v_mfma_f32_16x16x32_bf16 v[96:99], v[114:117], v[96:99], v[0:3]
	ds_read_b128 v[114:117], v130 offset:16384
	s_waitcnt lgkmcnt(0)
	v_mfma_f32_16x16x32_bf16 v[0:3], v[114:117], v[36:39], v[76:79]
	v_mfma_f32_16x16x32_bf16 v[4:7], v[118:121], v[36:39], v[68:71]
	v_mfma_f32_16x16x32_bf16 v[8:11], v[122:125], v[36:39], v[52:55]
	v_mfma_f32_16x16x32_bf16 v[36:39], v[132:135], v[36:39], v[40:43]
	v_mfma_f32_16x16x32_bf16 v[40:43], v[114:117], v[110:113], v[92:95]
	v_mfma_f32_16x16x32_bf16 v[52:55], v[118:121], v[110:113], v[100:103]
	v_mfma_f32_16x16x32_bf16 v[68:71], v[122:125], v[110:113], v[106:109]
	v_mfma_f32_16x16x32_bf16 v[76:79], v[132:135], v[110:113], v[96:99]
	s_waitcnt vmcnt(6)
	ds_write_b128 v87, v[12:15] offset:53248
	ds_write_b128 v87, v[16:19] offset:49152
	ds_write_b128 v87, v[20:23] offset:45056
	ds_write_b128 v87, v[28:31] offset:32768
	ds_write_b128 v87, v[32:35] offset:36864
	ds_write_b128 v87, v[24:27] offset:40960
	s_waitcnt lgkmcnt(0)
	s_barrier
	s_min_u32 s3, s2, 12
	s_lshl_b32 s92, s3, 7
	v_lshl_add_u64 v[12:13], v[80:81], 0, s[92:93]
	v_add_co_u32_e32 v14, vcc, s11, v12
	s_nop 1
	v_addc_co_u32_e32 v15, vcc, 0, v13, vcc
	global_load_dwordx4 v[28:31], v[12:13], off offset:384
	global_load_dwordx4 v[32:35], v[14:15], off offset:384
	v_add_co_u32_e32 v14, vcc, s33, v12
	s_nop 1
	v_addc_co_u32_e32 v15, vcc, 0, v13, vcc
	v_add_co_u32_e32 v12, vcc, s59, v12
	global_load_dwordx4 v[24:27], v[14:15], off offset:384
	s_nop 1
	v_addc_co_u32_e32 v13, vcc, 0, v13, vcc
	global_load_dwordx4 v[20:23], v[12:13], off offset:384
	v_lshl_add_u64 v[12:13], v[82:83], 0, s[92:93]
	global_load_dwordx4 v[16:19], v[12:13], off offset:384
	v_add_co_u32_e32 v12, vcc, s11, v12
	s_nop 1
	v_addc_co_u32_e32 v13, vcc, 0, v13, vcc
	global_load_dwordx4 v[12:15], v[12:13], off offset:384
	ds_read_b128 v[100:103], v127 offset:49152
	ds_read_b128 v[106:109], v127 offset:51200
	ds_read_b128 v[110:113], v127 offset:53248
	ds_read_b128 v[114:117], v127 offset:55296
	ds_read_b128 v[92:95], v126 offset:32768
	ds_read_b128 v[96:99], v126 offset:34816
	ds_read_b128 v[118:121], v130 offset:51200
	ds_read_b128 v[122:125], v130 offset:53248
	ds_read_b128 v[132:135], v130 offset:55296
	s_waitcnt lgkmcnt(4)
	v_mfma_f32_16x16x32_bf16 v[0:3], v[100:103], v[92:95], v[0:3]
	v_mfma_f32_16x16x32_bf16 v[4:7], v[106:109], v[92:95], v[4:7]
	v_mfma_f32_16x16x32_bf16 v[8:11], v[110:113], v[92:95], v[8:11]
	v_mfma_f32_16x16x32_bf16 v[36:39], v[114:117], v[92:95], v[36:39]
	s_waitcnt lgkmcnt(3)
	v_mfma_f32_16x16x32_bf16 v[92:95], v[100:103], v[96:99], v[40:43]
	s_nop 2
	ds_read_b128 v[40:43], v128 offset:32768
	v_mfma_f32_16x16x32_bf16 v[100:103], v[106:109], v[96:99], v[52:55]
	v_mfma_f32_16x16x32_bf16 v[106:109], v[110:113], v[96:99], v[68:71]
	ds_read_b128 v[110:113], v128 offset:34816
	v_mfma_f32_16x16x32_bf16 v[96:99], v[114:117], v[96:99], v[76:79]
	ds_read_b128 v[114:117], v130 offset:49152
	s_waitcnt lgkmcnt(0)
	v_mfma_f32_16x16x32_bf16 v[76:79], v[114:117], v[40:43], v[0:3]
	v_mfma_f32_16x16x32_bf16 v[68:71], v[118:121], v[40:43], v[4:7]
	v_mfma_f32_16x16x32_bf16 v[52:55], v[122:125], v[40:43], v[8:11]
	v_mfma_f32_16x16x32_bf16 v[40:43], v[132:135], v[40:43], v[36:39]
	v_mfma_f32_16x16x32_bf16 v[36:39], v[114:117], v[110:113], v[92:95]
	v_mfma_f32_16x16x32_bf16 v[8:11], v[118:121], v[110:113], v[100:103]
	v_mfma_f32_16x16x32_bf16 v[4:7], v[122:125], v[110:113], v[106:109]
	v_mfma_f32_16x16x32_bf16 v[0:3], v[132:135], v[110:113], v[96:99]
	s_waitcnt vmcnt(6)
	ds_write_b128 v87, v[44:47] offset:20480
	ds_write_b128 v87, v[48:51] offset:16384
	ds_write_b128 v87, v[56:59] offset:12288
	ds_write_b128 v87, v[72:75]
	ds_write_b128 v87, v[64:67] offset:4096
	ds_write_b128 v87, v[60:63] offset:8192
	s_cmp_lt_u32 s2, 12
	s_mov_b32 s3, s2
	s_waitcnt lgkmcnt(0)
	s_barrier
	s_cbranch_scc1 .LBB0_119
.Ltail119:
	s_add_i32 s2, s3, 2
	s_add_i32 s3, s3, 4
	s_min_u32 s3, s3, 15
	s_lshl_b32 s92, s3, 7
	v_add_u32_e32 v127, v89, v90
	ds_read_b128 v[100:103], v127 offset:16384
	ds_read_b128 v[106:109], v127 offset:18432
	ds_read_b128 v[110:113], v127 offset:20480
	ds_read_b128 v[114:117], v127 offset:22528
	v_add_u32_e32 v126, v88, v90
	ds_read_b128 v[92:95], v126
	ds_read_b128 v[96:99], v126 offset:2048
	v_add_u32_e32 v128, v88, v91
	v_add_u32_e32 v130, v89, v91
	ds_read_b128 v[118:121], v130 offset:18432
	ds_read_b128 v[122:125], v130 offset:20480
	ds_read_b128 v[132:135], v130 offset:22528
	s_waitcnt lgkmcnt(4)
	v_mfma_f32_16x16x32_bf16 v[76:79], v[100:103], v[92:95], v[76:79]
	v_mfma_f32_16x16x32_bf16 v[68:71], v[106:109], v[92:95], v[68:71]
	v_mfma_f32_16x16x32_bf16 v[52:55], v[110:113], v[92:95], v[52:55]
	v_mfma_f32_16x16x32_bf16 v[40:43], v[114:117], v[92:95], v[40:43]
	s_waitcnt lgkmcnt(3)
	v_mfma_f32_16x16x32_bf16 v[92:95], v[100:103], v[96:99], v[36:39]
	s_nop 2
	ds_read_b128 v[36:39], v128
	v_mfma_f32_16x16x32_bf16 v[100:103], v[106:109], v[96:99], v[8:11]
	v_mfma_f32_16x16x32_bf16 v[106:109], v[110:113], v[96:99], v[4:7]
	ds_read_b128 v[110:113], v128 offset:2048
	v_mfma_f32_16x16x32_bf16 v[96:99], v[114:117], v[96:99], v[0:3]
	ds_read_b128 v[114:117], v130 offset:16384
	s_waitcnt lgkmcnt(0)
	v_mfma_f32_16x16x32_bf16 v[0:3], v[114:117], v[36:39], v[76:79]
	v_mfma_f32_16x16x32_bf16 v[4:7], v[118:121], v[36:39], v[68:71]
	v_mfma_f32_16x16x32_bf16 v[8:11], v[122:125], v[36:39], v[52:55]
	v_mfma_f32_16x16x32_bf16 v[36:39], v[132:135], v[36:39], v[40:43]
	v_mfma_f32_16x16x32_bf16 v[40:43], v[114:117], v[110:113], v[92:95]
	v_mfma_f32_16x16x32_bf16 v[52:55], v[118:121], v[110:113], v[100:103]
	v_mfma_f32_16x16x32_bf16 v[68:71], v[122:125], v[110:113], v[106:109]
	v_mfma_f32_16x16x32_bf16 v[76:79], v[132:135], v[110:113], v[96:99]
	s_waitcnt vmcnt(0)
	ds_write_b128 v87, v[12:15] offset:53248
	s_waitcnt vmcnt(1)
	ds_write_b128 v87, v[16:19] offset:49152
	s_waitcnt vmcnt(2)
	ds_write_b128 v87, v[20:23] offset:45056
	s_waitcnt vmcnt(5)
	ds_write_b128 v87, v[28:31] offset:32768
	s_waitcnt vmcnt(4)
	ds_write_b128 v87, v[32:35] offset:36864
	s_waitcnt vmcnt(3)
	ds_write_b128 v87, v[24:27] offset:40960
	s_waitcnt lgkmcnt(0)
	s_barrier
	s_min_u32 s3, s2, 12
	s_lshl_b32 s92, s3, 7
	ds_read_b128 v[100:103], v127 offset:49152
	ds_read_b128 v[106:109], v127 offset:51200
	ds_read_b128 v[110:113], v127 offset:53248
	ds_read_b128 v[114:117], v127 offset:55296
	ds_read_b128 v[92:95], v126 offset:32768
	ds_read_b128 v[96:99], v126 offset:34816
	ds_read_b128 v[118:121], v130 offset:51200
	ds_read_b128 v[122:125], v130 offset:53248
	ds_read_b128 v[132:135], v130 offset:55296
	s_waitcnt lgkmcnt(4)
	v_mfma_f32_16x16x32_bf16 v[0:3], v[100:103], v[92:95], v[0:3]
	v_mfma_f32_16x16x32_bf16 v[4:7], v[106:109], v[92:95], v[4:7]
	v_mfma_f32_16x16x32_bf16 v[8:11], v[110:113], v[92:95], v[8:11]
	v_mfma_f32_16x16x32_bf16 v[36:39], v[114:117], v[92:95], v[36:39]
	s_waitcnt lgkmcnt(3)
	v_mfma_f32_16x16x32_bf16 v[92:95], v[100:103], v[96:99], v[40:43]
	s_nop 2
	ds_read_b128 v[40:43], v128 offset:32768
	v_mfma_f32_16x16x32_bf16 v[100:103], v[106:109], v[96:99], v[52:55]
	v_mfma_f32_16x16x32_bf16 v[106:109], v[110:113], v[96:99], v[68:71]
	ds_read_b128 v[110:113], v128 offset:34816
	v_mfma_f32_16x16x32_bf16 v[96:99], v[114:117], v[96:99], v[76:79]
	ds_read_b128 v[114:117], v130 offset:49152
	s_waitcnt lgkmcnt(0)
	v_mfma_f32_16x16x32_bf16 v[76:79], v[114:117], v[40:43], v[0:3]
	v_mfma_f32_16x16x32_bf16 v[68:71], v[118:121], v[40:43], v[4:7]
	v_mfma_f32_16x16x32_bf16 v[52:55], v[122:125], v[40:43], v[8:11]
	v_mfma_f32_16x16x32_bf16 v[40:43], v[132:135], v[40:43], v[36:39]
	v_mfma_f32_16x16x32_bf16 v[36:39], v[114:117], v[110:113], v[92:95]
	v_mfma_f32_16x16x32_bf16 v[8:11], v[118:121], v[110:113], v[100:103]
	v_mfma_f32_16x16x32_bf16 v[4:7], v[122:125], v[110:113], v[106:109]
	v_mfma_f32_16x16x32_bf16 v[0:3], v[132:135], v[110:113], v[96:99]
	s_mov_b32 s3, s2
	s_waitcnt lgkmcnt(0)
	s_barrier
	v_readlane_b32 s2, v251, 18
	s_waitcnt vmcnt(1)
	s_nop 0
	v_add_u32_e32 v18, s2, v86
	v_readlane_b32 s2, v251, 19
	s_waitcnt vmcnt(0)
	v_add_u32_e32 v13, 0xffffe000, v18
	v_or_b32_e32 v12, v18, v85
	v_lshl_or_b32 v19, v84, 2, s2
	v_lshrrev_b32_e32 v13, 10, v13
	s_movk_i32 s2, 0x1800
	v_mad_u32_u24 v13, v13, s2, s2
	v_cmp_lt_i32_e32 vcc, s13, v12
	v_lshlrev_b32_e32 v128, 2, v19
	v_readlane_b32 s2, v250, 15
	v_cndmask_b32_e32 v14, 0, v13, vcc
	v_ashrrev_i32_e32 v15, 31, v14
	v_lshlrev_b64 v[24:25], 2, v[14:15]
	v_ashrrev_i32_e32 v13, 31, v12
	v_lshl_add_u64 v[14:15], s[40:41], 0, v[24:25]
	v_lshl_add_u64 v[48:49], v[14:15], 0, v[128:129]
	v_lshlrev_b64 v[14:15], 12, v[12:13]
	v_readlane_b32 s3, v250, 16
	v_lshl_add_u64 v[28:29], s[42:43], 0, v[24:25]
	v_lshlrev_b64 v[32:33], 11, v[12:13]
	v_lshl_add_u64 v[14:15], s[2:3], 0, v[14:15]
	v_lshl_add_u64 v[50:51], v[14:15], 0, v[128:129]
	global_load_dwordx4 v[72:75], v[48:49], off
	global_load_dwordx4 v[80:83], v[48:49], off offset:64
	global_load_dwordx4 v[88:91], v[48:49], off offset:128
	global_load_dwordx4 v[136:139], v[48:49], off offset:192
	global_load_dwordx4 v[194:197], v[50:51], off
	global_load_dwordx4 v[198:201], v[50:51], off offset:64
	global_load_dwordx4 v[202:205], v[50:51], off offset:128
	global_load_dwordx4 v[206:209], v[50:51], off offset:192
	v_add_co_u32_e32 v58, vcc, 0x10000, v50
	s_nop 1
	v_addc_co_u32_e32 v59, vcc, 0, v51, vcc
	global_load_dwordx4 v[210:213], v[58:59], off
	global_load_dwordx4 v[214:217], v[58:59], off offset:64
	global_load_dwordx4 v[218:221], v[58:59], off offset:128
	global_load_dwordx4 v[222:225], v[58:59], off offset:192
	v_readlane_b32 s2, v250, 21
	v_readlane_b32 s3, v250, 22
	v_cmp_eq_u32_e32 vcc, 0, v84
	s_waitcnt vmcnt(4)
	v_pk_fma_f32 v[22:23], v[78:79], v[74:75], v[196:197]
	v_pk_fma_f32 v[20:21], v[76:77], v[72:73], v[194:195]
	global_store_dwordx4 v[50:51], v[20:23], off
	v_lshl_add_u64 v[14:15], v[28:29], 0, v[128:129]
	global_load_dwordx4 v[140:143], v128, s[0:1]
	global_load_dwordx4 v[144:147], v128, s[0:1] offset:64
	global_load_dwordx4 v[148:151], v128, s[0:1] offset:128
	global_load_dwordx4 v[152:155], v128, s[0:1] offset:192
	global_load_dwordx4 v[156:159], v[14:15], off
	global_load_dwordx4 v[160:163], v[14:15], off offset:64
	global_load_dwordx4 v[180:183], v[14:15], off offset:128
	global_load_dwordx4 v[190:193], v[14:15], off offset:192
	v_lshlrev_b32_e32 v16, 1, v19
	v_mov_b32_e32 v17, v129
	v_lshl_add_u64 v[32:33], s[2:3], 0, v[32:33]
	v_lshl_add_u64 v[56:57], v[32:33], 0, v[16:17]
	s_waitcnt vmcnt(0)
	v_pk_mul_f32 v[26:27], v[22:23], v[142:143]
	v_pk_mul_f32 v[24:25], v[20:21], v[140:141]
	s_waitcnt vmcnt(0)
	v_pk_add_f32 v[30:31], v[158:159], 1.0 op_sel_hi:[1,0]
	v_pk_add_f32 v[28:29], v[156:157], 1.0 op_sel_hi:[1,0]
	v_pk_mul_f32 v[26:27], v[26:27], v[30:31]
	v_pk_mul_f32 v[24:25], v[24:25], v[28:29]
	v_and_b32_sdwa v19, v26, v170 dst_sel:DWORD dst_unused:UNUSED_PAD src0_sel:WORD_1 src1_sel:DWORD
	v_and_b32_sdwa v29, v27, v170 dst_sel:DWORD dst_unused:UNUSED_PAD src0_sel:WORD_1 src1_sel:DWORD
	v_and_b32_sdwa v30, v25, v170 dst_sel:DWORD dst_unused:UNUSED_PAD src0_sel:WORD_1 src1_sel:DWORD
	v_and_b32_sdwa v28, v24, v170 dst_sel:DWORD dst_unused:UNUSED_PAD src0_sel:WORD_1 src1_sel:DWORD
	v_add3_u32 v19, v26, v19, s56
	v_add3_u32 v26, v27, v29, s56
	v_add3_u32 v25, v25, v30, s56
	v_add3_u32 v24, v24, v28, s56
	v_and_b32_e32 v26, 0xffff0000, v26
	v_and_b32_e32 v27, 0xffff0000, v25
	v_or_b32_sdwa v25, v26, v19 dst_sel:DWORD dst_unused:UNUSED_PAD src0_sel:DWORD src1_sel:WORD_1
	v_or_b32_sdwa v24, v27, v24 dst_sel:DWORD dst_unused:UNUSED_PAD src0_sel:DWORD src1_sel:WORD_1
	global_store_dwordx2 v[56:57], v[24:25], off
	s_nop 0
	s_waitcnt vmcnt(0)
	v_pk_fma_f32 v[26:27], v[70:71], v[82:83], v[200:201]
	v_pk_fma_f32 v[24:25], v[68:69], v[80:81], v[198:199]
	global_store_dwordx4 v[50:51], v[24:27], off offset:64
	v_pk_mul_f32 v[30:31], v[26:27], v[146:147]
	v_pk_mul_f32 v[28:29], v[24:25], v[144:145]
	v_pk_add_f32 v[34:35], v[162:163], 1.0 op_sel_hi:[1,0]
	v_pk_add_f32 v[32:33], v[160:161], 1.0 op_sel_hi:[1,0]
	v_pk_mul_f32 v[30:31], v[30:31], v[34:35]
	v_pk_mul_f32 v[28:29], v[28:29], v[32:33]
	v_and_b32_sdwa v19, v30, v170 dst_sel:DWORD dst_unused:UNUSED_PAD src0_sel:WORD_1 src1_sel:DWORD
	v_and_b32_sdwa v33, v31, v170 dst_sel:DWORD dst_unused:UNUSED_PAD src0_sel:WORD_1 src1_sel:DWORD
	v_and_b32_sdwa v34, v29, v170 dst_sel:DWORD dst_unused:UNUSED_PAD src0_sel:WORD_1 src1_sel:DWORD
	v_and_b32_sdwa v32, v28, v170 dst_sel:DWORD dst_unused:UNUSED_PAD src0_sel:WORD_1 src1_sel:DWORD
	v_add3_u32 v19, v30, v19, s56
	v_add3_u32 v30, v31, v33, s56
	v_add3_u32 v29, v29, v34, s56
	v_add3_u32 v28, v28, v32, s56
	v_and_b32_e32 v30, 0xffff0000, v30
	v_and_b32_e32 v31, 0xffff0000, v29
	v_or_b32_sdwa v29, v30, v19 dst_sel:DWORD dst_unused:UNUSED_PAD src0_sel:DWORD src1_sel:WORD_1
	v_or_b32_sdwa v28, v31, v28 dst_sel:DWORD dst_unused:UNUSED_PAD src0_sel:DWORD src1_sel:WORD_1
	global_store_dwordx2 v[56:57], v[28:29], off offset:32
	s_nop 0
	v_pk_fma_f32 v[30:31], v[54:55], v[90:91], v[204:205]
	v_pk_fma_f32 v[28:29], v[52:53], v[88:89], v[202:203]
	global_store_dwordx4 v[50:51], v[28:31], off offset:128
	v_pk_mul_f32 v[34:35], v[30:31], v[150:151]
	v_pk_mul_f32 v[32:33], v[28:29], v[148:149]
	v_pk_add_f32 v[46:47], v[182:183], 1.0 op_sel_hi:[1,0]
	v_pk_add_f32 v[44:45], v[180:181], 1.0 op_sel_hi:[1,0]
	v_pk_mul_f32 v[34:35], v[34:35], v[46:47]
	v_pk_mul_f32 v[32:33], v[32:33], v[44:45]
	v_and_b32_sdwa v19, v34, v170 dst_sel:DWORD dst_unused:UNUSED_PAD src0_sel:WORD_1 src1_sel:DWORD
	v_and_b32_sdwa v45, v35, v170 dst_sel:DWORD dst_unused:UNUSED_PAD src0_sel:WORD_1 src1_sel:DWORD
	v_and_b32_sdwa v46, v33, v170 dst_sel:DWORD dst_unused:UNUSED_PAD src0_sel:WORD_1 src1_sel:DWORD
	v_and_b32_sdwa v44, v32, v170 dst_sel:DWORD dst_unused:UNUSED_PAD src0_sel:WORD_1 src1_sel:DWORD
	v_add3_u32 v19, v34, v19, s56
	v_add3_u32 v34, v35, v45, s56
	v_add3_u32 v33, v33, v46, s56
	v_add3_u32 v32, v32, v44, s56
	v_and_b32_e32 v34, 0xffff0000, v34
	v_and_b32_e32 v35, 0xffff0000, v33
	v_or_b32_sdwa v33, v34, v19 dst_sel:DWORD dst_unused:UNUSED_PAD src0_sel:DWORD src1_sel:WORD_1
	v_or_b32_sdwa v32, v35, v32 dst_sel:DWORD dst_unused:UNUSED_PAD src0_sel:DWORD src1_sel:WORD_1
	global_store_dwordx2 v[56:57], v[32:33], off offset:64
	s_nop 0
	v_pk_fma_f32 v[34:35], v[42:43], v[138:139], v[208:209]
	v_pk_fma_f32 v[32:33], v[40:41], v[136:137], v[206:207]
	global_store_dwordx4 v[50:51], v[32:35], off offset:192
	v_mul_f32_e32 v14, v21, v21
	v_mul_f32_e32 v15, v25, v25
	v_fmac_f32_e32 v14, v20, v20
	v_fmac_f32_e32 v15, v24, v24
	v_fmac_f32_e32 v14, v22, v22
	v_fmac_f32_e32 v15, v26, v26
	v_fmac_f32_e32 v14, v23, v23
	v_fmac_f32_e32 v15, v27, v27
	v_add_f32_e32 v14, v14, v15
	v_mul_f32_e32 v15, v29, v29
	v_fmac_f32_e32 v15, v28, v28
	v_fmac_f32_e32 v15, v30, v30
	v_fmac_f32_e32 v15, v31, v31
	v_add_f32_e32 v14, v14, v15
	v_mul_f32_e32 v15, v33, v33
	v_fmac_f32_e32 v15, v32, v32
	v_fmac_f32_e32 v15, v34, v34
	v_fmac_f32_e32 v15, v35, v35
	v_add_f32_e32 v14, v14, v15
	ds_bpermute_b32 v15, v105, v14
	s_waitcnt lgkmcnt(0)
	v_add_f32_e32 v14, v14, v15
	ds_bpermute_b32 v15, v104, v14
	v_pk_mul_f32 v[20:21], v[34:35], v[154:155]
	v_pk_mul_f32 v[22:23], v[32:33], v[152:153]
	v_pk_add_f32 v[24:25], v[192:193], 1.0 op_sel_hi:[1,0]
	v_pk_add_f32 v[26:27], v[190:191], 1.0 op_sel_hi:[1,0]
	v_pk_mul_f32 v[20:21], v[20:21], v[24:25]
	v_pk_mul_f32 v[22:23], v[22:23], v[26:27]
	v_and_b32_sdwa v19, v20, v170 dst_sel:DWORD dst_unused:UNUSED_PAD src0_sel:WORD_1 src1_sel:DWORD
	v_and_b32_sdwa v25, v21, v170 dst_sel:DWORD dst_unused:UNUSED_PAD src0_sel:WORD_1 src1_sel:DWORD
	v_and_b32_sdwa v26, v23, v170 dst_sel:DWORD dst_unused:UNUSED_PAD src0_sel:WORD_1 src1_sel:DWORD
	v_and_b32_sdwa v24, v22, v170 dst_sel:DWORD dst_unused:UNUSED_PAD src0_sel:WORD_1 src1_sel:DWORD
	v_add3_u32 v19, v20, v19, s56
	v_add3_u32 v20, v21, v25, s56
	v_add3_u32 v21, v23, v26, s56
	v_add3_u32 v22, v22, v24, s56
	v_and_b32_e32 v20, 0xffff0000, v20
	v_and_b32_e32 v23, 0xffff0000, v21
	v_or_b32_sdwa v21, v20, v19 dst_sel:DWORD dst_unused:UNUSED_PAD src0_sel:DWORD src1_sel:WORD_1
	v_or_b32_sdwa v20, v23, v22 dst_sel:DWORD dst_unused:UNUSED_PAD src0_sel:DWORD src1_sel:WORD_1
	global_store_dwordx2 v[56:57], v[20:21], off offset:96
	s_and_saveexec_b64 s[2:3], vcc
	s_cbranch_execz .LBB0_122
	v_readlane_b32 s16, v253, 20
	s_add_u32 s24, s26, s16
	s_addc_u32 s25, s27, 0
	v_lshl_add_u64 v[20:21], v[12:13], 2, s[24:25]
	s_waitcnt lgkmcnt(0)
	v_add_f32_e32 v13, v14, v15
	global_store_dword v[20:21], v13, off

.LBB0_327:
	s_add_i32 s0, s1, 2
	s_add_i32 s1, s1, 4
	s_min_u32 s1, s1, 63
	s_lshl_b32 s92, s1, 7
	v_lshl_add_u64 v[48:49], v[80:81], 0, s[92:93]
	v_add_co_u32_e32 v50, vcc, s7, v48
	s_nop 1
	v_addc_co_u32_e32 v51, vcc, 0, v49, vcc
	global_load_dwordx4 v[72:75], v[48:49], off
	global_load_dwordx4 v[68:71], v[50:51], off
	v_add_co_u32_e32 v50, vcc, s52, v48
	s_nop 1
	v_addc_co_u32_e32 v51, vcc, 0, v49, vcc
	v_add_co_u32_e32 v48, vcc, s34, v48
	global_load_dwordx4 v[64:67], v[50:51], off
	s_nop 1
	v_addc_co_u32_e32 v49, vcc, 0, v49, vcc
	global_load_dwordx4 v[60:63], v[48:49], off
	v_lshl_add_u64 v[48:49], v[82:83], 0, s[92:93]
	global_load_dwordx4 v[52:55], v[48:49], off
	v_add_co_u32_e32 v48, vcc, s7, v48
	s_nop 1
	v_addc_co_u32_e32 v49, vcc, 0, v49, vcc
	global_load_dwordx4 v[48:51], v[48:49], off
	v_add_u32_e32 v127, v89, v90
	ds_read_b128 v[100:103], v127 offset:16384
	ds_read_b128 v[106:109], v127 offset:18432
	ds_read_b128 v[110:113], v127 offset:20480
	ds_read_b128 v[114:117], v127 offset:22528
	v_add_u32_e32 v126, v88, v90
	ds_read_b128 v[92:95], v126
	ds_read_b128 v[96:99], v126 offset:2048
	v_add_u32_e32 v128, v88, v91
	v_add_u32_e32 v130, v89, v91
	ds_read_b128 v[118:121], v130 offset:18432
	ds_read_b128 v[122:125], v130 offset:20480
	ds_read_b128 v[132:135], v130 offset:22528
	s_waitcnt lgkmcnt(4)
	v_mfma_f32_16x16x32_bf16 v[76:79], v[100:103], v[92:95], v[76:79]
	v_mfma_f32_16x16x32_bf16 v[56:59], v[106:109], v[92:95], v[56:59]
	v_mfma_f32_16x16x32_bf16 v[44:47], v[110:113], v[92:95], v[44:47]
	v_mfma_f32_16x16x32_bf16 v[24:27], v[114:117], v[92:95], v[24:27]
	s_waitcnt lgkmcnt(3)
	v_mfma_f32_16x16x32_bf16 v[92:95], v[100:103], v[96:99], v[12:15]
	s_nop 2
	ds_read_b128 v[12:15], v128
	v_mfma_f32_16x16x32_bf16 v[100:103], v[106:109], v[96:99], v[8:11]
	v_mfma_f32_16x16x32_bf16 v[106:109], v[110:113], v[96:99], v[4:7]
	ds_read_b128 v[110:113], v128 offset:2048
	v_mfma_f32_16x16x32_bf16 v[96:99], v[114:117], v[96:99], v[0:3]
	ds_read_b128 v[114:117], v130 offset:16384
	s_waitcnt lgkmcnt(0)
	v_mfma_f32_16x16x32_bf16 v[0:3], v[114:117], v[12:15], v[76:79]
	v_mfma_f32_16x16x32_bf16 v[4:7], v[118:121], v[12:15], v[56:59]
	v_mfma_f32_16x16x32_bf16 v[8:11], v[122:125], v[12:15], v[44:47]
	v_mfma_f32_16x16x32_bf16 v[12:15], v[132:135], v[12:15], v[24:27]
	v_mfma_f32_16x16x32_bf16 v[24:27], v[114:117], v[110:113], v[92:95]
	v_mfma_f32_16x16x32_bf16 v[44:47], v[118:121], v[110:113], v[100:103]
	v_mfma_f32_16x16x32_bf16 v[56:59], v[122:125], v[110:113], v[106:109]
	v_mfma_f32_16x16x32_bf16 v[76:79], v[132:135], v[110:113], v[96:99]
	s_waitcnt vmcnt(6)
	ds_write_b128 v87, v[16:19] offset:53248
	ds_write_b128 v87, v[20:23] offset:49152
	ds_write_b128 v87, v[28:31] offset:45056
	ds_write_b128 v87, v[36:39] offset:32768
	ds_write_b128 v87, v[40:43] offset:36864
	ds_write_b128 v87, v[32:35] offset:40960
	s_waitcnt lgkmcnt(0)
	s_barrier
	s_min_u32 s1, s0, 60
	s_lshl_b32 s92, s1, 7
	v_lshl_add_u64 v[16:17], v[80:81], 0, s[92:93]
	v_add_co_u32_e32 v18, vcc, s7, v16
	s_nop 1
	v_addc_co_u32_e32 v19, vcc, 0, v17, vcc
	global_load_dwordx4 v[36:39], v[16:17], off offset:384
	global_load_dwordx4 v[40:43], v[18:19], off offset:384
	v_add_co_u32_e32 v18, vcc, s52, v16
	s_nop 1
	v_addc_co_u32_e32 v19, vcc, 0, v17, vcc
	v_add_co_u32_e32 v16, vcc, s34, v16
	global_load_dwordx4 v[32:35], v[18:19], off offset:384
	s_nop 1
	v_addc_co_u32_e32 v17, vcc, 0, v17, vcc
	global_load_dwordx4 v[28:31], v[16:17], off offset:384
	v_lshl_add_u64 v[16:17], v[82:83], 0, s[92:93]
	global_load_dwordx4 v[20:23], v[16:17], off offset:384
	v_add_co_u32_e32 v16, vcc, s7, v16
	s_nop 1
	v_addc_co_u32_e32 v17, vcc, 0, v17, vcc
	global_load_dwordx4 v[16:19], v[16:17], off offset:384
	ds_read_b128 v[100:103], v127 offset:49152
	ds_read_b128 v[106:109], v127 offset:51200
	ds_read_b128 v[110:113], v127 offset:53248
	ds_read_b128 v[114:117], v127 offset:55296
	ds_read_b128 v[92:95], v126 offset:32768
	ds_read_b128 v[96:99], v126 offset:34816
	ds_read_b128 v[118:121], v130 offset:51200
	ds_read_b128 v[122:125], v130 offset:53248
	ds_read_b128 v[132:135], v130 offset:55296
	s_waitcnt lgkmcnt(4)
	v_mfma_f32_16x16x32_bf16 v[0:3], v[100:103], v[92:95], v[0:3]
	v_mfma_f32_16x16x32_bf16 v[4:7], v[106:109], v[92:95], v[4:7]
	v_mfma_f32_16x16x32_bf16 v[8:11], v[110:113], v[92:95], v[8:11]
	v_mfma_f32_16x16x32_bf16 v[12:15], v[114:117], v[92:95], v[12:15]
	s_waitcnt lgkmcnt(3)
	v_mfma_f32_16x16x32_bf16 v[92:95], v[100:103], v[96:99], v[24:27]
	s_nop 2
	ds_read_b128 v[24:27], v128 offset:32768
	v_mfma_f32_16x16x32_bf16 v[100:103], v[106:109], v[96:99], v[44:47]
	v_mfma_f32_16x16x32_bf16 v[106:109], v[110:113], v[96:99], v[56:59]
	ds_read_b128 v[110:113], v128 offset:34816
	v_mfma_f32_16x16x32_bf16 v[96:99], v[114:117], v[96:99], v[76:79]
	ds_read_b128 v[114:117], v130 offset:49152
	s_waitcnt lgkmcnt(0)
	v_mfma_f32_16x16x32_bf16 v[76:79], v[114:117], v[24:27], v[0:3]
	v_mfma_f32_16x16x32_bf16 v[56:59], v[118:121], v[24:27], v[4:7]
	v_mfma_f32_16x16x32_bf16 v[44:47], v[122:125], v[24:27], v[8:11]
	v_mfma_f32_16x16x32_bf16 v[24:27], v[132:135], v[24:27], v[12:15]
	v_mfma_f32_16x16x32_bf16 v[12:15], v[114:117], v[110:113], v[92:95]
	v_mfma_f32_16x16x32_bf16 v[8:11], v[118:121], v[110:113], v[100:103]
	v_mfma_f32_16x16x32_bf16 v[4:7], v[122:125], v[110:113], v[106:109]
	v_mfma_f32_16x16x32_bf16 v[0:3], v[132:135], v[110:113], v[96:99]
	s_waitcnt vmcnt(6)
	ds_write_b128 v87, v[48:51] offset:20480
	ds_write_b128 v87, v[52:55] offset:16384
	ds_write_b128 v87, v[60:63] offset:12288
	ds_write_b128 v87, v[72:75]
	ds_write_b128 v87, v[68:71] offset:4096
	ds_write_b128 v87, v[64:67] offset:8192
	s_cmp_lt_u32 s0, 60
	s_mov_b32 s1, s0
	s_waitcnt lgkmcnt(0)
	s_barrier
	s_cbranch_scc1 .LBB0_327
.Ltail327:
	s_add_i32 s0, s1, 2
	s_add_i32 s1, s1, 4
	s_min_u32 s1, s1, 63
	s_lshl_b32 s92, s1, 7
	v_add_u32_e32 v127, v89, v90
	ds_read_b128 v[100:103], v127 offset:16384
	ds_read_b128 v[106:109], v127 offset:18432
	ds_read_b128 v[110:113], v127 offset:20480
	ds_read_b128 v[114:117], v127 offset:22528
	v_add_u32_e32 v126, v88, v90
	ds_read_b128 v[92:95], v126
	ds_read_b128 v[96:99], v126 offset:2048
	v_add_u32_e32 v128, v88, v91
	v_add_u32_e32 v130, v89, v91
	ds_read_b128 v[118:121], v130 offset:18432
	ds_read_b128 v[122:125], v130 offset:20480
	ds_read_b128 v[132:135], v130 offset:22528
	s_waitcnt lgkmcnt(4)
	v_mfma_f32_16x16x32_bf16 v[76:79], v[100:103], v[92:95], v[76:79]
	v_mfma_f32_16x16x32_bf16 v[56:59], v[106:109], v[92:95], v[56:59]
	v_mfma_f32_16x16x32_bf16 v[44:47], v[110:113], v[92:95], v[44:47]
	v_mfma_f32_16x16x32_bf16 v[24:27], v[114:117], v[92:95], v[24:27]
	s_waitcnt lgkmcnt(3)
	v_mfma_f32_16x16x32_bf16 v[92:95], v[100:103], v[96:99], v[12:15]
	s_nop 2
	ds_read_b128 v[12:15], v128
	v_mfma_f32_16x16x32_bf16 v[100:103], v[106:109], v[96:99], v[8:11]
	v_mfma_f32_16x16x32_bf16 v[106:109], v[110:113], v[96:99], v[4:7]
	ds_read_b128 v[110:113], v128 offset:2048
	v_mfma_f32_16x16x32_bf16 v[96:99], v[114:117], v[96:99], v[0:3]
	ds_read_b128 v[114:117], v130 offset:16384
	s_waitcnt lgkmcnt(0)
	v_mfma_f32_16x16x32_bf16 v[0:3], v[114:117], v[12:15], v[76:79]
	v_mfma_f32_16x16x32_bf16 v[4:7], v[118:121], v[12:15], v[56:59]
	v_mfma_f32_16x16x32_bf16 v[8:11], v[122:125], v[12:15], v[44:47]
	v_mfma_f32_16x16x32_bf16 v[12:15], v[132:135], v[12:15], v[24:27]
	v_mfma_f32_16x16x32_bf16 v[24:27], v[114:117], v[110:113], v[92:95]
	v_mfma_f32_16x16x32_bf16 v[44:47], v[118:121], v[110:113], v[100:103]
	v_mfma_f32_16x16x32_bf16 v[56:59], v[122:125], v[110:113], v[106:109]
	v_mfma_f32_16x16x32_bf16 v[76:79], v[132:135], v[110:113], v[96:99]
	s_waitcnt vmcnt(0)
	ds_write_b128 v87, v[16:19] offset:53248
	s_waitcnt vmcnt(1)
	ds_write_b128 v87, v[20:23] offset:49152
	s_waitcnt vmcnt(2)
	ds_write_b128 v87, v[28:31] offset:45056
	s_waitcnt vmcnt(5)
	ds_write_b128 v87, v[36:39] offset:32768
	s_waitcnt vmcnt(4)
	ds_write_b128 v87, v[40:43] offset:36864
	s_waitcnt vmcnt(3)
	ds_write_b128 v87, v[32:35] offset:40960
	s_waitcnt lgkmcnt(0)
	s_barrier
	s_min_u32 s1, s0, 60
	s_lshl_b32 s92, s1, 7
	ds_read_b128 v[100:103], v127 offset:49152
	ds_read_b128 v[106:109], v127 offset:51200
	ds_read_b128 v[110:113], v127 offset:53248
	ds_read_b128 v[114:117], v127 offset:55296
	ds_read_b128 v[92:95], v126 offset:32768
	ds_read_b128 v[96:99], v126 offset:34816
	ds_read_b128 v[118:121], v130 offset:51200
	ds_read_b128 v[122:125], v130 offset:53248
	ds_read_b128 v[132:135], v130 offset:55296
	s_waitcnt lgkmcnt(4)
	v_mfma_f32_16x16x32_bf16 v[0:3], v[100:103], v[92:95], v[0:3]
	v_mfma_f32_16x16x32_bf16 v[4:7], v[106:109], v[92:95], v[4:7]
	v_mfma_f32_16x16x32_bf16 v[8:11], v[110:113], v[92:95], v[8:11]
	v_mfma_f32_16x16x32_bf16 v[12:15], v[114:117], v[92:95], v[12:15]
	s_waitcnt lgkmcnt(3)
	v_mfma_f32_16x16x32_bf16 v[92:95], v[100:103], v[96:99], v[24:27]
	s_nop 2
	ds_read_b128 v[24:27], v128 offset:32768
	v_mfma_f32_16x16x32_bf16 v[100:103], v[106:109], v[96:99], v[44:47]
	v_mfma_f32_16x16x32_bf16 v[106:109], v[110:113], v[96:99], v[56:59]
	ds_read_b128 v[110:113], v128 offset:34816
	v_mfma_f32_16x16x32_bf16 v[96:99], v[114:117], v[96:99], v[76:79]
	ds_read_b128 v[114:117], v130 offset:49152
	s_waitcnt lgkmcnt(0)
	v_mfma_f32_16x16x32_bf16 v[76:79], v[114:117], v[24:27], v[0:3]
	v_mfma_f32_16x16x32_bf16 v[56:59], v[118:121], v[24:27], v[4:7]
	v_mfma_f32_16x16x32_bf16 v[44:47], v[122:125], v[24:27], v[8:11]
	v_mfma_f32_16x16x32_bf16 v[24:27], v[132:135], v[24:27], v[12:15]
	v_mfma_f32_16x16x32_bf16 v[12:15], v[114:117], v[110:113], v[92:95]
	v_mfma_f32_16x16x32_bf16 v[8:11], v[118:121], v[110:113], v[100:103]
	v_mfma_f32_16x16x32_bf16 v[4:7], v[122:125], v[110:113], v[106:109]
	v_mfma_f32_16x16x32_bf16 v[0:3], v[132:135], v[110:113], v[96:99]
	s_mov_b32 s1, s0
	s_waitcnt lgkmcnt(0)
	s_barrier
	v_readlane_b32 s0, v251, 18
	s_nop 1
	v_add_u32_e32 v48, s0, v86
	v_readlane_b32 s0, v251, 19
	s_waitcnt vmcnt(0)
	v_add_u32_e32 v16, 0xffffe000, v48
	v_or_b32_e32 v34, v48, v85
	v_lshl_or_b32 v32, v84, 2, s0
	v_lshrrev_b32_e32 v16, 10, v16
	s_movk_i32 s0, 0x1800
	v_mad_u32_u24 v16, v16, s0, s0
	v_cmp_lt_i32_e32 vcc, s13, v34
	v_ashrrev_i32_e32 v35, 31, v34
	v_lshlrev_b32_e32 v128, 2, v32
	v_cndmask_b32_e32 v28, 0, v16, vcc
	v_ashrrev_i32_e32 v29, 31, v28
	v_lshl_add_u64 v[16:17], v[28:29], 2, s[40:41]
	v_readlane_b32 s0, v250, 15
	v_lshl_add_u64 v[40:41], v[16:17], 0, v[128:129]
	v_lshlrev_b64 v[16:17], 12, v[34:35]
	v_readlane_b32 s1, v250, 16
	v_lshlrev_b64 v[30:31], 10, v[34:35]
	s_and_b64 vcc, exec, s[36:37]
	v_lshl_add_u64 v[16:17], s[0:1], 0, v[16:17]
	v_lshl_add_u64 v[38:39], v[16:17], 0, v[128:129]
	global_load_dwordx4 v[60:63], v[40:41], off
	global_load_dwordx4 v[72:75], v[40:41], off offset:64
	global_load_dwordx4 v[80:83], v[40:41], off offset:128
	global_load_dwordx4 v[88:91], v[40:41], off offset:192
	global_load_dwordx4 v[190:193], v[38:39], off
	global_load_dwordx4 v[194:197], v[38:39], off offset:64
	global_load_dwordx4 v[198:201], v[38:39], off offset:128
	global_load_dwordx4 v[202:205], v[38:39], off offset:192
	v_add_co_u32_e32 v54, vcc, 0x10000, v38
	s_nop 1
	v_addc_co_u32_e32 v55, vcc, 0, v39, vcc
	global_load_dwordx4 v[206:209], v[54:55], off
	global_load_dwordx4 v[210:213], v[54:55], off offset:64
	global_load_dwordx4 v[214:217], v[54:55], off offset:128
	global_load_dwordx4 v[218:221], v[54:55], off offset:192
	v_readlane_b32 s0, v250, 21
	v_readlane_b32 s1, v250, 22
	v_lshl_add_u64 v[42:43], v[28:29], 2, s[42:43]
	v_lshlrev_b32_e32 v32, 1, v32
	v_lshl_add_u64 v[36:37], v[30:31], 1, s[0:1]
	s_waitcnt vmcnt(4)
	v_pk_fma_f32 v[18:19], v[78:79], v[62:63], v[192:193]
	v_pk_fma_f32 v[16:17], v[76:77], v[60:61], v[190:191]
	global_store_dwordx4 v[38:39], v[16:19], off
	s_cbranch_vccnz .LBB0_330
	v_lshl_add_u64 v[28:29], v[42:43], 0, v[128:129]
	global_load_dwordx4 v[136:139], v128, s[26:27]
	global_load_dwordx4 v[140:143], v128, s[26:27] offset:64
	global_load_dwordx4 v[144:147], v128, s[26:27] offset:128
	global_load_dwordx4 v[148:151], v128, s[26:27] offset:192
	v_mov_b32_e32 v33, v129
	global_load_dwordx4 v[152:155], v[28:29], off
	global_load_dwordx4 v[156:159], v[28:29], off offset:64
	global_load_dwordx4 v[160:163], v[28:29], off offset:128
	global_load_dwordx4 v[180:183], v[28:29], off offset:192
	s_waitcnt vmcnt(0)
	v_pk_mul_f32 v[22:23], v[18:19], v[138:139]
	v_pk_mul_f32 v[20:21], v[16:17], v[136:137]
	s_waitcnt vmcnt(0)
	v_pk_add_f32 v[30:31], v[154:155], 1.0 op_sel_hi:[1,0]
	v_pk_add_f32 v[28:29], v[152:153], 1.0 op_sel_hi:[1,0]
	v_pk_mul_f32 v[22:23], v[22:23], v[30:31]
	v_pk_mul_f32 v[20:21], v[20:21], v[28:29]
	v_and_b32_sdwa v30, v22, v170 dst_sel:DWORD dst_unused:UNUSED_PAD src0_sel:WORD_1 src1_sel:DWORD
	v_and_b32_sdwa v31, v20, v170 dst_sel:DWORD dst_unused:UNUSED_PAD src0_sel:WORD_1 src1_sel:DWORD
	v_add3_u32 v20, v20, v31, s56
	v_add3_u32 v22, v22, v30, s56
	v_and_b32_sdwa v30, v23, v170 dst_sel:DWORD dst_unused:UNUSED_PAD src0_sel:WORD_1 src1_sel:DWORD
	v_and_b32_sdwa v31, v21, v170 dst_sel:DWORD dst_unused:UNUSED_PAD src0_sel:WORD_1 src1_sel:DWORD
	v_add3_u32 v23, v23, v30, s56
	v_add3_u32 v21, v21, v31, s56
	v_and_b32_e32 v23, 0xffff0000, v23
	v_and_b32_e32 v30, 0xffff0000, v21
	v_lshl_add_u64 v[28:29], v[36:37], 0, v[32:33]
	v_or_b32_sdwa v21, v23, v22 dst_sel:DWORD dst_unused:UNUSED_PAD src0_sel:DWORD src1_sel:WORD_1
	v_or_b32_sdwa v20, v30, v20 dst_sel:DWORD dst_unused:UNUSED_PAD src0_sel:DWORD src1_sel:WORD_1
	global_store_dwordx2 v[28:29], v[20:21], off

.Ltail419:
	s_add_i32 s2, s3, 2
	s_add_i32 s3, s3, 4
	s_min_u32 s3, s3, 15
	s_lshl_b32 s92, s3, 7
	v_add_u32_e32 v127, v89, v90
	ds_read_b128 v[100:103], v127 offset:16384
	ds_read_b128 v[106:109], v127 offset:18432
	ds_read_b128 v[110:113], v127 offset:20480
	ds_read_b128 v[114:117], v127 offset:22528
	v_add_u32_e32 v126, v88, v90
	ds_read_b128 v[92:95], v126
	ds_read_b128 v[96:99], v126 offset:2048
	v_add_u32_e32 v128, v88, v91
	v_add_u32_e32 v130, v89, v91
	ds_read_b128 v[118:121], v130 offset:18432
	ds_read_b128 v[122:125], v130 offset:20480
	ds_read_b128 v[132:135], v130 offset:22528
	s_waitcnt lgkmcnt(4)
	v_mfma_f32_16x16x32_bf16 v[76:79], v[100:103], v[92:95], v[76:79]
	v_mfma_f32_16x16x32_bf16 v[68:71], v[106:109], v[92:95], v[68:71]
	v_mfma_f32_16x16x32_bf16 v[52:55], v[110:113], v[92:95], v[52:55]
	v_mfma_f32_16x16x32_bf16 v[40:43], v[114:117], v[92:95], v[40:43]
	s_waitcnt lgkmcnt(3)
	v_mfma_f32_16x16x32_bf16 v[92:95], v[100:103], v[96:99], v[36:39]
	s_nop 2
	ds_read_b128 v[36:39], v128
	v_mfma_f32_16x16x32_bf16 v[100:103], v[106:109], v[96:99], v[8:11]
	v_mfma_f32_16x16x32_bf16 v[106:109], v[110:113], v[96:99], v[4:7]
	ds_read_b128 v[110:113], v128 offset:2048
	v_mfma_f32_16x16x32_bf16 v[96:99], v[114:117], v[96:99], v[0:3]
	ds_read_b128 v[114:117], v130 offset:16384
	s_waitcnt lgkmcnt(0)
	v_mfma_f32_16x16x32_bf16 v[0:3], v[114:117], v[36:39], v[76:79]
	v_mfma_f32_16x16x32_bf16 v[4:7], v[118:121], v[36:39], v[68:71]
	v_mfma_f32_16x16x32_bf16 v[8:11], v[122:125], v[36:39], v[52:55]
	v_mfma_f32_16x16x32_bf16 v[36:39], v[132:135], v[36:39], v[40:43]
	v_mfma_f32_16x16x32_bf16 v[40:43], v[114:117], v[110:113], v[92:95]
	v_mfma_f32_16x16x32_bf16 v[52:55], v[118:121], v[110:113], v[100:103]
	v_mfma_f32_16x16x32_bf16 v[68:71], v[122:125], v[110:113], v[106:109]
	v_mfma_f32_16x16x32_bf16 v[76:79], v[132:135], v[110:113], v[96:99]
	s_waitcnt vmcnt(0)
	ds_write_b128 v87, v[12:15] offset:53248
	s_waitcnt vmcnt(1)
	ds_write_b128 v87, v[16:19] offset:49152
	s_waitcnt vmcnt(2)
	ds_write_b128 v87, v[20:23] offset:45056
	s_waitcnt vmcnt(5)
	ds_write_b128 v87, v[28:31] offset:32768
	s_waitcnt vmcnt(4)
	ds_write_b128 v87, v[32:35] offset:36864
	s_waitcnt vmcnt(3)
	ds_write_b128 v87, v[24:27] offset:40960
	s_waitcnt lgkmcnt(0)
	s_barrier
	s_min_u32 s3, s2, 12
	s_lshl_b32 s92, s3, 7
	ds_read_b128 v[100:103], v127 offset:49152
	ds_read_b128 v[106:109], v127 offset:51200
	ds_read_b128 v[110:113], v127 offset:53248
	ds_read_b128 v[114:117], v127 offset:55296
	ds_read_b128 v[92:95], v126 offset:32768
	ds_read_b128 v[96:99], v126 offset:34816
	ds_read_b128 v[118:121], v130 offset:51200
	ds_read_b128 v[122:125], v130 offset:53248
	ds_read_b128 v[132:135], v130 offset:55296
	s_waitcnt lgkmcnt(4)
	v_mfma_f32_16x16x32_bf16 v[0:3], v[100:103], v[92:95], v[0:3]
	v_mfma_f32_16x16x32_bf16 v[4:7], v[106:109], v[92:95], v[4:7]
	v_mfma_f32_16x16x32_bf16 v[8:11], v[110:113], v[92:95], v[8:11]
	v_mfma_f32_16x16x32_bf16 v[36:39], v[114:117], v[92:95], v[36:39]
	s_waitcnt lgkmcnt(3)
	v_mfma_f32_16x16x32_bf16 v[92:95], v[100:103], v[96:99], v[40:43]
	s_nop 2
	ds_read_b128 v[40:43], v128 offset:32768
	v_mfma_f32_16x16x32_bf16 v[100:103], v[106:109], v[96:99], v[52:55]
	v_mfma_f32_16x16x32_bf16 v[106:109], v[110:113], v[96:99], v[68:71]
	ds_read_b128 v[110:113], v128 offset:34816
	v_mfma_f32_16x16x32_bf16 v[96:99], v[114:117], v[96:99], v[76:79]
	ds_read_b128 v[114:117], v130 offset:49152
	s_waitcnt lgkmcnt(0)
	v_mfma_f32_16x16x32_bf16 v[76:79], v[114:117], v[40:43], v[0:3]
	v_mfma_f32_16x16x32_bf16 v[68:71], v[118:121], v[40:43], v[4:7]
	v_mfma_f32_16x16x32_bf16 v[52:55], v[122:125], v[40:43], v[8:11]
	v_mfma_f32_16x16x32_bf16 v[40:43], v[132:135], v[40:43], v[36:39]
	v_mfma_f32_16x16x32_bf16 v[36:39], v[114:117], v[110:113], v[92:95]
	v_mfma_f32_16x16x32_bf16 v[8:11], v[118:121], v[110:113], v[100:103]
	v_mfma_f32_16x16x32_bf16 v[4:7], v[122:125], v[110:113], v[106:109]
	v_mfma_f32_16x16x32_bf16 v[0:3], v[132:135], v[110:113], v[96:99]
	s_mov_b32 s3, s2
	s_waitcnt lgkmcnt(0)
	s_barrier
	v_readlane_b32 s2, v251, 18
	s_waitcnt vmcnt(1)
	s_nop 0
	v_add_u32_e32 v18, s2, v86
	v_readlane_b32 s2, v251, 19
	s_waitcnt vmcnt(0)
	v_add_u32_e32 v13, 0xffffe000, v18
	v_or_b32_e32 v12, v18, v85
	v_lshl_or_b32 v19, v84, 2, s2
	v_lshrrev_b32_e32 v13, 10, v13
	s_movk_i32 s2, 0x1800
	v_mad_u32_u24 v13, v13, s2, s2
	v_cmp_lt_i32_e32 vcc, s13, v12
	v_lshlrev_b32_e32 v128, 2, v19
	v_readlane_b32 s2, v250, 15
	v_cndmask_b32_e32 v14, 0, v13, vcc
	v_ashrrev_i32_e32 v15, 31, v14
	v_lshlrev_b64 v[24:25], 2, v[14:15]
	v_ashrrev_i32_e32 v13, 31, v12
	v_lshl_add_u64 v[14:15], s[40:41], 0, v[24:25]
	v_lshl_add_u64 v[48:49], v[14:15], 0, v[128:129]
	v_lshlrev_b64 v[14:15], 12, v[12:13]
	v_readlane_b32 s3, v250, 16
	v_lshl_add_u64 v[28:29], s[42:43], 0, v[24:25]
	v_lshlrev_b64 v[32:33], 11, v[12:13]
	v_lshl_add_u64 v[14:15], s[2:3], 0, v[14:15]
	v_lshl_add_u64 v[50:51], v[14:15], 0, v[128:129]
	global_load_dwordx4 v[72:75], v[48:49], off
	global_load_dwordx4 v[80:83], v[48:49], off offset:64
	global_load_dwordx4 v[88:91], v[48:49], off offset:128
	global_load_dwordx4 v[136:139], v[48:49], off offset:192
	global_load_dwordx4 v[194:197], v[50:51], off
	global_load_dwordx4 v[198:201], v[50:51], off offset:64
	global_load_dwordx4 v[202:205], v[50:51], off offset:128
	global_load_dwordx4 v[206:209], v[50:51], off offset:192
	v_add_co_u32_e32 v58, vcc, 0x10000, v50
	s_nop 1
	v_addc_co_u32_e32 v59, vcc, 0, v51, vcc
	global_load_dwordx4 v[210:213], v[58:59], off
	global_load_dwordx4 v[214:217], v[58:59], off offset:64
	global_load_dwordx4 v[218:221], v[58:59], off offset:128
	global_load_dwordx4 v[222:225], v[58:59], off offset:192
	v_readlane_b32 s2, v250, 21
	v_readlane_b32 s3, v250, 22
	v_cmp_eq_u32_e32 vcc, 0, v84
	s_waitcnt vmcnt(4)
	v_pk_fma_f32 v[22:23], v[78:79], v[74:75], v[196:197]
	v_pk_fma_f32 v[20:21], v[76:77], v[72:73], v[194:195]
	global_store_dwordx4 v[50:51], v[20:23], off
	v_lshl_add_u64 v[14:15], v[28:29], 0, v[128:129]
	global_load_dwordx4 v[140:143], v128, s[0:1]
	global_load_dwordx4 v[144:147], v128, s[0:1] offset:64
	global_load_dwordx4 v[148:151], v128, s[0:1] offset:128
	global_load_dwordx4 v[152:155], v128, s[0:1] offset:192
	global_load_dwordx4 v[156:159], v[14:15], off
	global_load_dwordx4 v[160:163], v[14:15], off offset:64
	global_load_dwordx4 v[180:183], v[14:15], off offset:128
	global_load_dwordx4 v[190:193], v[14:15], off offset:192
	v_lshlrev_b32_e32 v16, 1, v19
	v_mov_b32_e32 v17, v129
	v_lshl_add_u64 v[32:33], s[2:3], 0, v[32:33]
	v_lshl_add_u64 v[56:57], v[32:33], 0, v[16:17]
	s_waitcnt vmcnt(0)
	v_pk_mul_f32 v[26:27], v[22:23], v[142:143]
	v_pk_mul_f32 v[24:25], v[20:21], v[140:141]
	s_waitcnt vmcnt(0)
	v_pk_add_f32 v[30:31], v[158:159], 1.0 op_sel_hi:[1,0]
	v_pk_add_f32 v[28:29], v[156:157], 1.0 op_sel_hi:[1,0]
	v_pk_mul_f32 v[26:27], v[26:27], v[30:31]
	v_pk_mul_f32 v[24:25], v[24:25], v[28:29]
	v_and_b32_sdwa v19, v26, v170 dst_sel:DWORD dst_unused:UNUSED_PAD src0_sel:WORD_1 src1_sel:DWORD
	v_and_b32_sdwa v29, v27, v170 dst_sel:DWORD dst_unused:UNUSED_PAD src0_sel:WORD_1 src1_sel:DWORD
	v_and_b32_sdwa v30, v25, v170 dst_sel:DWORD dst_unused:UNUSED_PAD src0_sel:WORD_1 src1_sel:DWORD
	v_and_b32_sdwa v28, v24, v170 dst_sel:DWORD dst_unused:UNUSED_PAD src0_sel:WORD_1 src1_sel:DWORD
	v_add3_u32 v19, v26, v19, s56
	v_add3_u32 v26, v27, v29, s56
	v_add3_u32 v25, v25, v30, s56
	v_add3_u32 v24, v24, v28, s56
	v_and_b32_e32 v26, 0xffff0000, v26
	v_and_b32_e32 v27, 0xffff0000, v25
	v_or_b32_sdwa v25, v26, v19 dst_sel:DWORD dst_unused:UNUSED_PAD src0_sel:DWORD src1_sel:WORD_1
	v_or_b32_sdwa v24, v27, v24 dst_sel:DWORD dst_unused:UNUSED_PAD src0_sel:DWORD src1_sel:WORD_1
	global_store_dwordx2 v[56:57], v[24:25], off
	s_nop 0
	s_waitcnt vmcnt(0)
	v_pk_fma_f32 v[26:27], v[70:71], v[82:83], v[200:201]
	v_pk_fma_f32 v[24:25], v[68:69], v[80:81], v[198:199]
	global_store_dwordx4 v[50:51], v[24:27], off offset:64
	v_pk_mul_f32 v[30:31], v[26:27], v[146:147]
	v_pk_mul_f32 v[28:29], v[24:25], v[144:145]
	v_pk_add_f32 v[34:35], v[162:163], 1.0 op_sel_hi:[1,0]
	v_pk_add_f32 v[32:33], v[160:161], 1.0 op_sel_hi:[1,0]
	v_pk_mul_f32 v[30:31], v[30:31], v[34:35]
	v_pk_mul_f32 v[28:29], v[28:29], v[32:33]
	v_and_b32_sdwa v19, v30, v170 dst_sel:DWORD dst_unused:UNUSED_PAD src0_sel:WORD_1 src1_sel:DWORD
	v_and_b32_sdwa v33, v31, v170 dst_sel:DWORD dst_unused:UNUSED_PAD src0_sel:WORD_1 src1_sel:DWORD
	v_and_b32_sdwa v34, v29, v170 dst_sel:DWORD dst_unused:UNUSED_PAD src0_sel:WORD_1 src1_sel:DWORD
	v_and_b32_sdwa v32, v28, v170 dst_sel:DWORD dst_unused:UNUSED_PAD src0_sel:WORD_1 src1_sel:DWORD
	v_add3_u32 v19, v30, v19, s56
	v_add3_u32 v30, v31, v33, s56
	v_add3_u32 v29, v29, v34, s56
	v_add3_u32 v28, v28, v32, s56
	v_and_b32_e32 v30, 0xffff0000, v30
	v_and_b32_e32 v31, 0xffff0000, v29
	v_or_b32_sdwa v29, v30, v19 dst_sel:DWORD dst_unused:UNUSED_PAD src0_sel:DWORD src1_sel:WORD_1
	v_or_b32_sdwa v28, v31, v28 dst_sel:DWORD dst_unused:UNUSED_PAD src0_sel:DWORD src1_sel:WORD_1
	global_store_dwordx2 v[56:57], v[28:29], off offset:32
	s_nop 0
	v_pk_fma_f32 v[30:31], v[54:55], v[90:91], v[204:205]
	v_pk_fma_f32 v[28:29], v[52:53], v[88:89], v[202:203]
	global_store_dwordx4 v[50:51], v[28:31], off offset:128
	v_pk_mul_f32 v[34:35], v[30:31], v[150:151]
	v_pk_mul_f32 v[32:33], v[28:29], v[148:149]
	v_pk_add_f32 v[46:47], v[182:183], 1.0 op_sel_hi:[1,0]
	v_pk_add_f32 v[44:45], v[180:181], 1.0 op_sel_hi:[1,0]
	v_pk_mul_f32 v[34:35], v[34:35], v[46:47]
	v_pk_mul_f32 v[32:33], v[32:33], v[44:45]
	v_and_b32_sdwa v19, v34, v170 dst_sel:DWORD dst_unused:UNUSED_PAD src0_sel:WORD_1 src1_sel:DWORD
	v_and_b32_sdwa v45, v35, v170 dst_sel:DWORD dst_unused:UNUSED_PAD src0_sel:WORD_1 src1_sel:DWORD
	v_and_b32_sdwa v46, v33, v170 dst_sel:DWORD dst_unused:UNUSED_PAD src0_sel:WORD_1 src1_sel:DWORD
	v_and_b32_sdwa v44, v32, v170 dst_sel:DWORD dst_unused:UNUSED_PAD src0_sel:WORD_1 src1_sel:DWORD
	v_add3_u32 v19, v34, v19, s56
	v_add3_u32 v34, v35, v45, s56
	v_add3_u32 v33, v33, v46, s56
	v_add3_u32 v32, v32, v44, s56
	v_and_b32_e32 v34, 0xffff0000, v34
	v_and_b32_e32 v35, 0xffff0000, v33
	v_or_b32_sdwa v33, v34, v19 dst_sel:DWORD dst_unused:UNUSED_PAD src0_sel:DWORD src1_sel:WORD_1
	v_or_b32_sdwa v32, v35, v32 dst_sel:DWORD dst_unused:UNUSED_PAD src0_sel:DWORD src1_sel:WORD_1
	global_store_dwordx2 v[56:57], v[32:33], off offset:64
	s_nop 0
	v_pk_fma_f32 v[34:35], v[42:43], v[138:139], v[208:209]
	v_pk_fma_f32 v[32:33], v[40:41], v[136:137], v[206:207]
	global_store_dwordx4 v[50:51], v[32:35], off offset:192
	v_mul_f32_e32 v14, v21, v21
	v_mul_f32_e32 v15, v25, v25
	v_fmac_f32_e32 v14, v20, v20
	v_fmac_f32_e32 v15, v24, v24
	v_fmac_f32_e32 v14, v22, v22
	v_fmac_f32_e32 v15, v26, v26
	v_fmac_f32_e32 v14, v23, v23
	v_fmac_f32_e32 v15, v27, v27
	v_add_f32_e32 v14, v14, v15
	v_mul_f32_e32 v15, v29, v29
	v_fmac_f32_e32 v15, v28, v28
	v_fmac_f32_e32 v15, v30, v30
	v_fmac_f32_e32 v15, v31, v31
	v_add_f32_e32 v14, v14, v15
	v_mul_f32_e32 v15, v33, v33
	v_fmac_f32_e32 v15, v32, v32
	v_fmac_f32_e32 v15, v34, v34
	v_fmac_f32_e32 v15, v35, v35
	v_add_f32_e32 v14, v14, v15
	ds_bpermute_b32 v15, v105, v14
	s_waitcnt lgkmcnt(0)
	v_add_f32_e32 v14, v14, v15
	ds_bpermute_b32 v15, v104, v14
	v_pk_mul_f32 v[20:21], v[34:35], v[154:155]
	v_pk_mul_f32 v[22:23], v[32:33], v[152:153]
	v_pk_add_f32 v[24:25], v[192:193], 1.0 op_sel_hi:[1,0]
	v_pk_add_f32 v[26:27], v[190:191], 1.0 op_sel_hi:[1,0]
	v_pk_mul_f32 v[20:21], v[20:21], v[24:25]
	v_pk_mul_f32 v[22:23], v[22:23], v[26:27]
	v_and_b32_sdwa v19, v20, v170 dst_sel:DWORD dst_unused:UNUSED_PAD src0_sel:WORD_1 src1_sel:DWORD
	v_and_b32_sdwa v25, v21, v170 dst_sel:DWORD dst_unused:UNUSED_PAD src0_sel:WORD_1 src1_sel:DWORD
	v_and_b32_sdwa v26, v23, v170 dst_sel:DWORD dst_unused:UNUSED_PAD src0_sel:WORD_1 src1_sel:DWORD
	v_and_b32_sdwa v24, v22, v170 dst_sel:DWORD dst_unused:UNUSED_PAD src0_sel:WORD_1 src1_sel:DWORD
	v_add3_u32 v19, v20, v19, s56
	v_add3_u32 v20, v21, v25, s56
	v_add3_u32 v21, v23, v26, s56
	v_add3_u32 v22, v22, v24, s56
	v_and_b32_e32 v20, 0xffff0000, v20
	v_and_b32_e32 v23, 0xffff0000, v21
	v_or_b32_sdwa v21, v20, v19 dst_sel:DWORD dst_unused:UNUSED_PAD src0_sel:DWORD src1_sel:WORD_1
	v_or_b32_sdwa v20, v23, v22 dst_sel:DWORD dst_unused:UNUSED_PAD src0_sel:DWORD src1_sel:WORD_1
	global_store_dwordx2 v[56:57], v[20:21], off offset:96
	s_and_saveexec_b64 s[2:3], vcc
	s_cbranch_execz .LBB0_422
	v_readlane_b32 s16, v253, 20
	s_add_u32 s24, s38, s16
	s_addc_u32 s25, s39, 0
	v_lshl_add_u64 v[20:21], v[12:13], 2, s[24:25]
	s_waitcnt lgkmcnt(0)
	v_add_f32_e32 v13, v14, v15
	global_store_dword v[20:21], v13, off

.LBB0_609:
	s_add_i32 s2, s3, 2
	s_add_i32 s3, s3, 4
	s_min_u32 s3, s3, 63
	s_lshl_b32 s92, s3, 7
	v_lshl_add_u64 v[44:45], v[80:81], 0, s[92:93]
	v_add_co_u32_e32 v46, vcc, s7, v44
	s_nop 1
	v_addc_co_u32_e32 v47, vcc, 0, v45, vcc
	global_load_dwordx4 v[72:75], v[44:45], off
	global_load_dwordx4 v[64:67], v[46:47], off
	v_add_co_u32_e32 v46, vcc, s52, v44
	s_nop 1
	v_addc_co_u32_e32 v47, vcc, 0, v45, vcc
	v_add_co_u32_e32 v44, vcc, s34, v44
	global_load_dwordx4 v[60:63], v[46:47], off
	s_nop 1
	v_addc_co_u32_e32 v45, vcc, 0, v45, vcc
	global_load_dwordx4 v[56:59], v[44:45], off
	v_lshl_add_u64 v[44:45], v[82:83], 0, s[92:93]
	global_load_dwordx4 v[48:51], v[44:45], off
	v_add_co_u32_e32 v44, vcc, s7, v44
	s_nop 1
	v_addc_co_u32_e32 v45, vcc, 0, v45, vcc
	global_load_dwordx4 v[44:47], v[44:45], off
	v_add_u32_e32 v127, v89, v90
	ds_read_b128 v[100:103], v127 offset:16384
	ds_read_b128 v[106:109], v127 offset:18432
	ds_read_b128 v[110:113], v127 offset:20480
	ds_read_b128 v[114:117], v127 offset:22528
	v_add_u32_e32 v126, v88, v90
	ds_read_b128 v[92:95], v126
	ds_read_b128 v[96:99], v126 offset:2048
	v_add_u32_e32 v128, v88, v91
	v_add_u32_e32 v130, v89, v91
	ds_read_b128 v[118:121], v130 offset:18432
	ds_read_b128 v[122:125], v130 offset:20480
	ds_read_b128 v[132:135], v130 offset:22528
	s_waitcnt lgkmcnt(4)
	v_mfma_f32_16x16x32_bf16 v[76:79], v[100:103], v[92:95], v[76:79]
	v_mfma_f32_16x16x32_bf16 v[68:71], v[106:109], v[92:95], v[68:71]
	v_mfma_f32_16x16x32_bf16 v[52:55], v[110:113], v[92:95], v[52:55]
	v_mfma_f32_16x16x32_bf16 v[40:43], v[114:117], v[92:95], v[40:43]
	s_waitcnt lgkmcnt(3)
	v_mfma_f32_16x16x32_bf16 v[92:95], v[100:103], v[96:99], v[36:39]
	s_nop 2
	ds_read_b128 v[36:39], v128
	v_mfma_f32_16x16x32_bf16 v[100:103], v[106:109], v[96:99], v[8:11]
	v_mfma_f32_16x16x32_bf16 v[106:109], v[110:113], v[96:99], v[4:7]
	ds_read_b128 v[110:113], v128 offset:2048
	v_mfma_f32_16x16x32_bf16 v[96:99], v[114:117], v[96:99], v[0:3]
	ds_read_b128 v[114:117], v130 offset:16384
	s_waitcnt lgkmcnt(0)
	v_mfma_f32_16x16x32_bf16 v[0:3], v[114:117], v[36:39], v[76:79]
	v_mfma_f32_16x16x32_bf16 v[4:7], v[118:121], v[36:39], v[68:71]
	v_mfma_f32_16x16x32_bf16 v[8:11], v[122:125], v[36:39], v[52:55]
	v_mfma_f32_16x16x32_bf16 v[36:39], v[132:135], v[36:39], v[40:43]
	v_mfma_f32_16x16x32_bf16 v[40:43], v[114:117], v[110:113], v[92:95]
	v_mfma_f32_16x16x32_bf16 v[52:55], v[118:121], v[110:113], v[100:103]
	v_mfma_f32_16x16x32_bf16 v[68:71], v[122:125], v[110:113], v[106:109]
	v_mfma_f32_16x16x32_bf16 v[76:79], v[132:135], v[110:113], v[96:99]
	s_waitcnt vmcnt(6)
	ds_write_b128 v87, v[12:15] offset:53248
	ds_write_b128 v87, v[16:19] offset:49152
	ds_write_b128 v87, v[20:23] offset:45056
	ds_write_b128 v87, v[28:31] offset:32768
	ds_write_b128 v87, v[32:35] offset:36864
	ds_write_b128 v87, v[24:27] offset:40960
	s_waitcnt lgkmcnt(0)
	s_barrier
	s_min_u32 s3, s2, 60
	s_lshl_b32 s92, s3, 7
	v_lshl_add_u64 v[12:13], v[80:81], 0, s[92:93]
	v_add_co_u32_e32 v14, vcc, s7, v12
	s_nop 1
	v_addc_co_u32_e32 v15, vcc, 0, v13, vcc
	global_load_dwordx4 v[28:31], v[12:13], off offset:384
	global_load_dwordx4 v[32:35], v[14:15], off offset:384
	v_add_co_u32_e32 v14, vcc, s52, v12
	s_nop 1
	v_addc_co_u32_e32 v15, vcc, 0, v13, vcc
	v_add_co_u32_e32 v12, vcc, s34, v12
	global_load_dwordx4 v[24:27], v[14:15], off offset:384
	s_nop 1
	v_addc_co_u32_e32 v13, vcc, 0, v13, vcc
	global_load_dwordx4 v[20:23], v[12:13], off offset:384
	v_lshl_add_u64 v[12:13], v[82:83], 0, s[92:93]
	global_load_dwordx4 v[16:19], v[12:13], off offset:384
	v_add_co_u32_e32 v12, vcc, s7, v12
	s_nop 1
	v_addc_co_u32_e32 v13, vcc, 0, v13, vcc
	global_load_dwordx4 v[12:15], v[12:13], off offset:384
	ds_read_b128 v[100:103], v127 offset:49152
	ds_read_b128 v[106:109], v127 offset:51200
	ds_read_b128 v[110:113], v127 offset:53248
	ds_read_b128 v[114:117], v127 offset:55296
	ds_read_b128 v[92:95], v126 offset:32768
	ds_read_b128 v[96:99], v126 offset:34816
	ds_read_b128 v[118:121], v130 offset:51200
	ds_read_b128 v[122:125], v130 offset:53248
	ds_read_b128 v[132:135], v130 offset:55296
	s_waitcnt lgkmcnt(4)
	v_mfma_f32_16x16x32_bf16 v[0:3], v[100:103], v[92:95], v[0:3]
	v_mfma_f32_16x16x32_bf16 v[4:7], v[106:109], v[92:95], v[4:7]
	v_mfma_f32_16x16x32_bf16 v[8:11], v[110:113], v[92:95], v[8:11]
	v_mfma_f32_16x16x32_bf16 v[36:39], v[114:117], v[92:95], v[36:39]
	s_waitcnt lgkmcnt(3)
	v_mfma_f32_16x16x32_bf16 v[92:95], v[100:103], v[96:99], v[40:43]
	s_nop 2
	ds_read_b128 v[40:43], v128 offset:32768
	v_mfma_f32_16x16x32_bf16 v[100:103], v[106:109], v[96:99], v[52:55]
	v_mfma_f32_16x16x32_bf16 v[106:109], v[110:113], v[96:99], v[68:71]
	ds_read_b128 v[110:113], v128 offset:34816
	v_mfma_f32_16x16x32_bf16 v[96:99], v[114:117], v[96:99], v[76:79]
	ds_read_b128 v[114:117], v130 offset:49152
	s_waitcnt lgkmcnt(0)
	v_mfma_f32_16x16x32_bf16 v[76:79], v[114:117], v[40:43], v[0:3]
	v_mfma_f32_16x16x32_bf16 v[68:71], v[118:121], v[40:43], v[4:7]
	v_mfma_f32_16x16x32_bf16 v[52:55], v[122:125], v[40:43], v[8:11]
	v_mfma_f32_16x16x32_bf16 v[40:43], v[132:135], v[40:43], v[36:39]
	v_mfma_f32_16x16x32_bf16 v[36:39], v[114:117], v[110:113], v[92:95]
	v_mfma_f32_16x16x32_bf16 v[8:11], v[118:121], v[110:113], v[100:103]
	v_mfma_f32_16x16x32_bf16 v[4:7], v[122:125], v[110:113], v[106:109]
	v_mfma_f32_16x16x32_bf16 v[0:3], v[132:135], v[110:113], v[96:99]
	s_waitcnt vmcnt(6)
	ds_write_b128 v87, v[44:47] offset:20480
	ds_write_b128 v87, v[48:51] offset:16384
	ds_write_b128 v87, v[56:59] offset:12288
	ds_write_b128 v87, v[72:75]
	ds_write_b128 v87, v[64:67] offset:4096
	ds_write_b128 v87, v[60:63] offset:8192
	s_cmp_lt_u32 s2, 60
	s_mov_b32 s3, s2
	s_waitcnt lgkmcnt(0)
	s_barrier
	s_cbranch_scc1 .LBB0_609
.Ltail609:
	s_add_i32 s2, s3, 2
	s_add_i32 s3, s3, 4
	s_min_u32 s3, s3, 63
	s_lshl_b32 s92, s3, 7
	v_add_u32_e32 v127, v89, v90
	ds_read_b128 v[100:103], v127 offset:16384
	ds_read_b128 v[106:109], v127 offset:18432
	ds_read_b128 v[110:113], v127 offset:20480
	ds_read_b128 v[114:117], v127 offset:22528
	v_add_u32_e32 v126, v88, v90
	ds_read_b128 v[92:95], v126
	ds_read_b128 v[96:99], v126 offset:2048
	v_add_u32_e32 v128, v88, v91
	v_add_u32_e32 v130, v89, v91
	ds_read_b128 v[118:121], v130 offset:18432
	ds_read_b128 v[122:125], v130 offset:20480
	ds_read_b128 v[132:135], v130 offset:22528
	s_waitcnt lgkmcnt(4)
	v_mfma_f32_16x16x32_bf16 v[76:79], v[100:103], v[92:95], v[76:79]
	v_mfma_f32_16x16x32_bf16 v[68:71], v[106:109], v[92:95], v[68:71]
	v_mfma_f32_16x16x32_bf16 v[52:55], v[110:113], v[92:95], v[52:55]
	v_mfma_f32_16x16x32_bf16 v[40:43], v[114:117], v[92:95], v[40:43]
	s_waitcnt lgkmcnt(3)
	v_mfma_f32_16x16x32_bf16 v[92:95], v[100:103], v[96:99], v[36:39]
	s_nop 2
	ds_read_b128 v[36:39], v128
	v_mfma_f32_16x16x32_bf16 v[100:103], v[106:109], v[96:99], v[8:11]
	v_mfma_f32_16x16x32_bf16 v[106:109], v[110:113], v[96:99], v[4:7]
	ds_read_b128 v[110:113], v128 offset:2048
	v_mfma_f32_16x16x32_bf16 v[96:99], v[114:117], v[96:99], v[0:3]
	ds_read_b128 v[114:117], v130 offset:16384
	s_waitcnt lgkmcnt(0)
	v_mfma_f32_16x16x32_bf16 v[0:3], v[114:117], v[36:39], v[76:79]
	v_mfma_f32_16x16x32_bf16 v[4:7], v[118:121], v[36:39], v[68:71]
	v_mfma_f32_16x16x32_bf16 v[8:11], v[122:125], v[36:39], v[52:55]
	v_mfma_f32_16x16x32_bf16 v[36:39], v[132:135], v[36:39], v[40:43]
	v_mfma_f32_16x16x32_bf16 v[40:43], v[114:117], v[110:113], v[92:95]
	v_mfma_f32_16x16x32_bf16 v[52:55], v[118:121], v[110:113], v[100:103]
	v_mfma_f32_16x16x32_bf16 v[68:71], v[122:125], v[110:113], v[106:109]
	v_mfma_f32_16x16x32_bf16 v[76:79], v[132:135], v[110:113], v[96:99]
	s_waitcnt vmcnt(0)
	ds_write_b128 v87, v[12:15] offset:53248
	s_waitcnt vmcnt(1)
	ds_write_b128 v87, v[16:19] offset:49152
	s_waitcnt vmcnt(2)
	ds_write_b128 v87, v[20:23] offset:45056
	s_waitcnt vmcnt(5)
	ds_write_b128 v87, v[28:31] offset:32768
	s_waitcnt vmcnt(4)
	ds_write_b128 v87, v[32:35] offset:36864
	s_waitcnt vmcnt(3)
	ds_write_b128 v87, v[24:27] offset:40960
	s_waitcnt lgkmcnt(0)
	s_barrier
	s_min_u32 s3, s2, 60
	s_lshl_b32 s92, s3, 7
	ds_read_b128 v[100:103], v127 offset:49152
	ds_read_b128 v[106:109], v127 offset:51200
	ds_read_b128 v[110:113], v127 offset:53248
	ds_read_b128 v[114:117], v127 offset:55296
	ds_read_b128 v[92:95], v126 offset:32768
	ds_read_b128 v[96:99], v126 offset:34816
	ds_read_b128 v[118:121], v130 offset:51200
	ds_read_b128 v[122:125], v130 offset:53248
	ds_read_b128 v[132:135], v130 offset:55296
	s_waitcnt lgkmcnt(4)
	v_mfma_f32_16x16x32_bf16 v[0:3], v[100:103], v[92:95], v[0:3]
	v_mfma_f32_16x16x32_bf16 v[4:7], v[106:109], v[92:95], v[4:7]
	v_mfma_f32_16x16x32_bf16 v[8:11], v[110:113], v[92:95], v[8:11]
	v_mfma_f32_16x16x32_bf16 v[36:39], v[114:117], v[92:95], v[36:39]
	s_waitcnt lgkmcnt(3)
	v_mfma_f32_16x16x32_bf16 v[92:95], v[100:103], v[96:99], v[40:43]
	s_nop 2
	ds_read_b128 v[40:43], v128 offset:32768
	v_mfma_f32_16x16x32_bf16 v[100:103], v[106:109], v[96:99], v[52:55]
	v_mfma_f32_16x16x32_bf16 v[106:109], v[110:113], v[96:99], v[68:71]
	ds_read_b128 v[110:113], v128 offset:34816
	v_mfma_f32_16x16x32_bf16 v[96:99], v[114:117], v[96:99], v[76:79]
	ds_read_b128 v[114:117], v130 offset:49152
	s_waitcnt lgkmcnt(0)
	v_mfma_f32_16x16x32_bf16 v[76:79], v[114:117], v[40:43], v[0:3]
	v_mfma_f32_16x16x32_bf16 v[68:71], v[118:121], v[40:43], v[4:7]
	v_mfma_f32_16x16x32_bf16 v[52:55], v[122:125], v[40:43], v[8:11]
	v_mfma_f32_16x16x32_bf16 v[40:43], v[132:135], v[40:43], v[36:39]
	v_mfma_f32_16x16x32_bf16 v[36:39], v[114:117], v[110:113], v[92:95]
	v_mfma_f32_16x16x32_bf16 v[8:11], v[118:121], v[110:113], v[100:103]
	v_mfma_f32_16x16x32_bf16 v[4:7], v[122:125], v[110:113], v[106:109]
	v_mfma_f32_16x16x32_bf16 v[0:3], v[132:135], v[110:113], v[96:99]
	s_mov_b32 s3, s2
	s_waitcnt lgkmcnt(0)
	s_barrier
	v_readlane_b32 s2, v251, 18
	s_waitcnt vmcnt(1)
	s_nop 0
	v_add_u32_e32 v18, s2, v86
	v_readlane_b32 s2, v251, 19
	s_waitcnt vmcnt(0)
	v_add_u32_e32 v13, 0xffffe000, v18
	v_or_b32_e32 v12, v18, v85
	v_lshl_or_b32 v19, v84, 2, s2
	v_lshrrev_b32_e32 v13, 10, v13
	s_movk_i32 s2, 0x1800
	v_mad_u32_u24 v13, v13, s2, s2
	v_cmp_lt_i32_e32 vcc, s13, v12
	v_lshlrev_b32_e32 v128, 2, v19
	v_readlane_b32 s2, v250, 15
	v_cndmask_b32_e32 v14, 0, v13, vcc
	v_ashrrev_i32_e32 v15, 31, v14
	v_lshlrev_b64 v[24:25], 2, v[14:15]
	v_ashrrev_i32_e32 v13, 31, v12
	v_lshl_add_u64 v[14:15], s[38:39], 0, v[24:25]
	v_lshl_add_u64 v[48:49], v[14:15], 0, v[128:129]
	v_lshlrev_b64 v[14:15], 12, v[12:13]
	v_readlane_b32 s3, v250, 16
	v_lshl_add_u64 v[28:29], s[40:41], 0, v[24:25]
	v_lshlrev_b64 v[32:33], 11, v[12:13]
	v_lshl_add_u64 v[14:15], s[2:3], 0, v[14:15]
	v_lshl_add_u64 v[50:51], v[14:15], 0, v[128:129]
	global_load_dwordx4 v[72:75], v[48:49], off
	global_load_dwordx4 v[80:83], v[48:49], off offset:64
	global_load_dwordx4 v[88:91], v[48:49], off offset:128
	global_load_dwordx4 v[136:139], v[48:49], off offset:192
	global_load_dwordx4 v[194:197], v[50:51], off
	global_load_dwordx4 v[198:201], v[50:51], off offset:64
	global_load_dwordx4 v[202:205], v[50:51], off offset:128
	global_load_dwordx4 v[206:209], v[50:51], off offset:192
	v_add_co_u32_e32 v58, vcc, 0x10000, v50
	s_nop 1
	v_addc_co_u32_e32 v59, vcc, 0, v51, vcc
	global_load_dwordx4 v[210:213], v[58:59], off
	global_load_dwordx4 v[214:217], v[58:59], off offset:64
	global_load_dwordx4 v[218:221], v[58:59], off offset:128
	global_load_dwordx4 v[222:225], v[58:59], off offset:192
	v_readlane_b32 s2, v250, 21
	v_readlane_b32 s3, v250, 22
	v_cmp_eq_u32_e32 vcc, 0, v84
	s_waitcnt vmcnt(4)
	v_pk_fma_f32 v[22:23], v[78:79], v[74:75], v[196:197]
	v_pk_fma_f32 v[20:21], v[76:77], v[72:73], v[194:195]
	global_store_dwordx4 v[50:51], v[20:23], off
	v_lshl_add_u64 v[14:15], v[28:29], 0, v[128:129]
	global_load_dwordx4 v[140:143], v128, s[0:1]
	global_load_dwordx4 v[144:147], v128, s[0:1] offset:64
	global_load_dwordx4 v[148:151], v128, s[0:1] offset:128
	global_load_dwordx4 v[152:155], v128, s[0:1] offset:192
	global_load_dwordx4 v[156:159], v[14:15], off
	global_load_dwordx4 v[160:163], v[14:15], off offset:64
	global_load_dwordx4 v[180:183], v[14:15], off offset:128
	global_load_dwordx4 v[190:193], v[14:15], off offset:192
	v_lshlrev_b32_e32 v16, 1, v19
	v_mov_b32_e32 v17, v129
	v_lshl_add_u64 v[32:33], s[2:3], 0, v[32:33]
	v_lshl_add_u64 v[56:57], v[32:33], 0, v[16:17]
	s_waitcnt vmcnt(0)
	v_pk_mul_f32 v[26:27], v[22:23], v[142:143]
	v_pk_mul_f32 v[24:25], v[20:21], v[140:141]
	s_waitcnt vmcnt(0)
	v_pk_add_f32 v[30:31], v[158:159], 1.0 op_sel_hi:[1,0]
	v_pk_add_f32 v[28:29], v[156:157], 1.0 op_sel_hi:[1,0]
	v_pk_mul_f32 v[26:27], v[26:27], v[30:31]
	v_pk_mul_f32 v[24:25], v[24:25], v[28:29]
	v_and_b32_sdwa v19, v26, v170 dst_sel:DWORD dst_unused:UNUSED_PAD src0_sel:WORD_1 src1_sel:DWORD
	v_and_b32_sdwa v29, v27, v170 dst_sel:DWORD dst_unused:UNUSED_PAD src0_sel:WORD_1 src1_sel:DWORD
	v_and_b32_sdwa v30, v25, v170 dst_sel:DWORD dst_unused:UNUSED_PAD src0_sel:WORD_1 src1_sel:DWORD
	v_and_b32_sdwa v28, v24, v170 dst_sel:DWORD dst_unused:UNUSED_PAD src0_sel:WORD_1 src1_sel:DWORD
	v_add3_u32 v19, v26, v19, s56
	v_add3_u32 v26, v27, v29, s56
	v_add3_u32 v25, v25, v30, s56
	v_add3_u32 v24, v24, v28, s56
	v_and_b32_e32 v26, 0xffff0000, v26
	v_and_b32_e32 v27, 0xffff0000, v25
	v_or_b32_sdwa v25, v26, v19 dst_sel:DWORD dst_unused:UNUSED_PAD src0_sel:DWORD src1_sel:WORD_1
	v_or_b32_sdwa v24, v27, v24 dst_sel:DWORD dst_unused:UNUSED_PAD src0_sel:DWORD src1_sel:WORD_1
	global_store_dwordx2 v[56:57], v[24:25], off
	s_nop 0
	s_waitcnt vmcnt(0)
	v_pk_fma_f32 v[26:27], v[70:71], v[82:83], v[200:201]
	v_pk_fma_f32 v[24:25], v[68:69], v[80:81], v[198:199]
	global_store_dwordx4 v[50:51], v[24:27], off offset:64
	v_pk_mul_f32 v[30:31], v[26:27], v[146:147]
	v_pk_mul_f32 v[28:29], v[24:25], v[144:145]
	v_pk_add_f32 v[34:35], v[162:163], 1.0 op_sel_hi:[1,0]
	v_pk_add_f32 v[32:33], v[160:161], 1.0 op_sel_hi:[1,0]
	v_pk_mul_f32 v[30:31], v[30:31], v[34:35]
	v_pk_mul_f32 v[28:29], v[28:29], v[32:33]
	v_and_b32_sdwa v19, v30, v170 dst_sel:DWORD dst_unused:UNUSED_PAD src0_sel:WORD_1 src1_sel:DWORD
	v_and_b32_sdwa v33, v31, v170 dst_sel:DWORD dst_unused:UNUSED_PAD src0_sel:WORD_1 src1_sel:DWORD
	v_and_b32_sdwa v34, v29, v170 dst_sel:DWORD dst_unused:UNUSED_PAD src0_sel:WORD_1 src1_sel:DWORD
	v_and_b32_sdwa v32, v28, v170 dst_sel:DWORD dst_unused:UNUSED_PAD src0_sel:WORD_1 src1_sel:DWORD
	v_add3_u32 v19, v30, v19, s56
	v_add3_u32 v30, v31, v33, s56
	v_add3_u32 v29, v29, v34, s56
	v_add3_u32 v28, v28, v32, s56
	v_and_b32_e32 v30, 0xffff0000, v30
	v_and_b32_e32 v31, 0xffff0000, v29
	v_or_b32_sdwa v29, v30, v19 dst_sel:DWORD dst_unused:UNUSED_PAD src0_sel:DWORD src1_sel:WORD_1
	v_or_b32_sdwa v28, v31, v28 dst_sel:DWORD dst_unused:UNUSED_PAD src0_sel:DWORD src1_sel:WORD_1
	global_store_dwordx2 v[56:57], v[28:29], off offset:32
	s_nop 0
	v_pk_fma_f32 v[30:31], v[54:55], v[90:91], v[204:205]
	v_pk_fma_f32 v[28:29], v[52:53], v[88:89], v[202:203]
	global_store_dwordx4 v[50:51], v[28:31], off offset:128
	v_pk_mul_f32 v[34:35], v[30:31], v[150:151]
	v_pk_mul_f32 v[32:33], v[28:29], v[148:149]
	v_pk_add_f32 v[46:47], v[182:183], 1.0 op_sel_hi:[1,0]
	v_pk_add_f32 v[44:45], v[180:181], 1.0 op_sel_hi:[1,0]
	v_pk_mul_f32 v[34:35], v[34:35], v[46:47]
	v_pk_mul_f32 v[32:33], v[32:33], v[44:45]
	v_and_b32_sdwa v19, v34, v170 dst_sel:DWORD dst_unused:UNUSED_PAD src0_sel:WORD_1 src1_sel:DWORD
	v_and_b32_sdwa v45, v35, v170 dst_sel:DWORD dst_unused:UNUSED_PAD src0_sel:WORD_1 src1_sel:DWORD
	v_and_b32_sdwa v46, v33, v170 dst_sel:DWORD dst_unused:UNUSED_PAD src0_sel:WORD_1 src1_sel:DWORD
	v_and_b32_sdwa v44, v32, v170 dst_sel:DWORD dst_unused:UNUSED_PAD src0_sel:WORD_1 src1_sel:DWORD
	v_add3_u32 v19, v34, v19, s56
	v_add3_u32 v34, v35, v45, s56
	v_add3_u32 v33, v33, v46, s56
	v_add3_u32 v32, v32, v44, s56
	v_and_b32_e32 v34, 0xffff0000, v34
	v_and_b32_e32 v35, 0xffff0000, v33
	v_or_b32_sdwa v33, v34, v19 dst_sel:DWORD dst_unused:UNUSED_PAD src0_sel:DWORD src1_sel:WORD_1
	v_or_b32_sdwa v32, v35, v32 dst_sel:DWORD dst_unused:UNUSED_PAD src0_sel:DWORD src1_sel:WORD_1
	global_store_dwordx2 v[56:57], v[32:33], off offset:64
	s_nop 0
	v_pk_fma_f32 v[34:35], v[42:43], v[138:139], v[208:209]
	v_pk_fma_f32 v[32:33], v[40:41], v[136:137], v[206:207]
	global_store_dwordx4 v[50:51], v[32:35], off offset:192
	v_mul_f32_e32 v14, v21, v21
	v_mul_f32_e32 v15, v25, v25
	v_fmac_f32_e32 v14, v20, v20
	v_fmac_f32_e32 v15, v24, v24
	v_fmac_f32_e32 v14, v22, v22
	v_fmac_f32_e32 v15, v26, v26
	v_fmac_f32_e32 v14, v23, v23
	v_fmac_f32_e32 v15, v27, v27
	v_add_f32_e32 v14, v14, v15
	v_mul_f32_e32 v15, v29, v29
	v_fmac_f32_e32 v15, v28, v28
	v_fmac_f32_e32 v15, v30, v30
	v_fmac_f32_e32 v15, v31, v31
	v_add_f32_e32 v14, v14, v15
	v_mul_f32_e32 v15, v33, v33
	v_fmac_f32_e32 v15, v32, v32
	v_fmac_f32_e32 v15, v34, v34
	v_fmac_f32_e32 v15, v35, v35
	v_add_f32_e32 v14, v14, v15
	ds_bpermute_b32 v15, v105, v14
	s_waitcnt lgkmcnt(0)
	v_add_f32_e32 v14, v14, v15
	ds_bpermute_b32 v15, v104, v14
	v_pk_mul_f32 v[20:21], v[34:35], v[154:155]
	v_pk_mul_f32 v[22:23], v[32:33], v[152:153]
	v_pk_add_f32 v[24:25], v[192:193], 1.0 op_sel_hi:[1,0]
	v_pk_add_f32 v[26:27], v[190:191], 1.0 op_sel_hi:[1,0]
	v_pk_mul_f32 v[20:21], v[20:21], v[24:25]
	v_pk_mul_f32 v[22:23], v[22:23], v[26:27]
	v_and_b32_sdwa v19, v20, v170 dst_sel:DWORD dst_unused:UNUSED_PAD src0_sel:WORD_1 src1_sel:DWORD
	v_and_b32_sdwa v25, v21, v170 dst_sel:DWORD dst_unused:UNUSED_PAD src0_sel:WORD_1 src1_sel:DWORD
	v_and_b32_sdwa v26, v23, v170 dst_sel:DWORD dst_unused:UNUSED_PAD src0_sel:WORD_1 src1_sel:DWORD
	v_and_b32_sdwa v24, v22, v170 dst_sel:DWORD dst_unused:UNUSED_PAD src0_sel:WORD_1 src1_sel:DWORD
	v_add3_u32 v19, v20, v19, s56
	v_add3_u32 v20, v21, v25, s56
	v_add3_u32 v21, v23, v26, s56
	v_add3_u32 v22, v22, v24, s56
	v_and_b32_e32 v20, 0xffff0000, v20
	v_and_b32_e32 v23, 0xffff0000, v21
	v_or_b32_sdwa v21, v20, v19 dst_sel:DWORD dst_unused:UNUSED_PAD src0_sel:DWORD src1_sel:WORD_1
	v_or_b32_sdwa v20, v23, v22 dst_sel:DWORD dst_unused:UNUSED_PAD src0_sel:DWORD src1_sel:WORD_1
	global_store_dwordx2 v[56:57], v[20:21], off offset:96
	s_and_saveexec_b64 s[2:3], vcc
	s_cbranch_execz .LBB0_612
	v_readlane_b32 s16, v253, 20
	s_add_u32 s24, s26, s16
	s_addc_u32 s25, s27, 0
	v_lshl_add_u64 v[20:21], v[12:13], 2, s[24:25]
	s_waitcnt lgkmcnt(0)
	v_add_f32_e32 v13, v14, v15
	global_store_dword v[20:21], v13, off

.LBB0_739:
	s_add_i32 s2, s3, 2
	s_add_i32 s3, s3, 4
	s_min_u32 s3, s3, 15
	s_lshl_b32 s92, s3, 7
	v_lshl_add_u64 v[52:53], v[80:81], 0, s[92:93]
	v_add_co_u32_e32 v54, vcc, s11, v52
	s_nop 1
	v_addc_co_u32_e32 v55, vcc, 0, v53, vcc
	global_load_dwordx4 v[76:79], v[52:53], off
	global_load_dwordx4 v[68:71], v[54:55], off
	v_add_co_u32_e32 v54, vcc, s33, v52
	s_nop 1
	v_addc_co_u32_e32 v55, vcc, 0, v53, vcc
	v_add_co_u32_e32 v52, vcc, s59, v52
	global_load_dwordx4 v[64:67], v[54:55], off
	s_nop 1
	v_addc_co_u32_e32 v53, vcc, 0, v53, vcc
	global_load_dwordx4 v[60:63], v[52:53], off
	v_lshl_add_u64 v[52:53], v[82:83], 0, s[92:93]
	global_load_dwordx4 v[56:59], v[52:53], off
	v_add_co_u32_e32 v52, vcc, s11, v52
	s_nop 1
	v_addc_co_u32_e32 v53, vcc, 0, v53, vcc
	global_load_dwordx4 v[52:55], v[52:53], off
	v_add_u32_e32 v130, v105, v106
	ds_read_b128 v[116:119], v130 offset:16384
	ds_read_b128 v[120:123], v130 offset:18432
	ds_read_b128 v[124:127], v130 offset:20480
	ds_read_b128 v[132:135], v130 offset:22528
	v_add_u32_e32 v128, v104, v106
	ds_read_b128 v[108:111], v128
	ds_read_b128 v[112:115], v128 offset:2048
	v_add_u32_e32 v148, v104, v107
	v_add_u32_e32 v149, v105, v107
	ds_read_b128 v[136:139], v149 offset:18432
	ds_read_b128 v[140:143], v149 offset:20480
	ds_read_b128 v[144:147], v149 offset:22528
	s_waitcnt lgkmcnt(4)
	v_mfma_f32_16x16x32_bf16 v[72:75], v[116:119], v[108:111], v[72:75]
	v_mfma_f32_16x16x32_bf16 v[48:51], v[120:123], v[108:111], v[48:51]
	v_mfma_f32_16x16x32_bf16 v[44:47], v[124:127], v[108:111], v[44:47]
	v_mfma_f32_16x16x32_bf16 v[40:43], v[132:135], v[108:111], v[40:43]
	s_waitcnt lgkmcnt(3)
	v_mfma_f32_16x16x32_bf16 v[108:111], v[116:119], v[112:115], v[16:19]
	s_nop 2
	ds_read_b128 v[16:19], v148
	v_mfma_f32_16x16x32_bf16 v[116:119], v[120:123], v[112:115], v[8:11]
	v_mfma_f32_16x16x32_bf16 v[120:123], v[124:127], v[112:115], v[4:7]
	ds_read_b128 v[124:127], v148 offset:2048
	v_mfma_f32_16x16x32_bf16 v[112:115], v[132:135], v[112:115], v[0:3]
	ds_read_b128 v[132:135], v149 offset:16384
	s_waitcnt lgkmcnt(0)
	v_mfma_f32_16x16x32_bf16 v[0:3], v[132:135], v[16:19], v[72:75]
	v_mfma_f32_16x16x32_bf16 v[4:7], v[136:139], v[16:19], v[48:51]
	v_mfma_f32_16x16x32_bf16 v[8:11], v[140:143], v[16:19], v[44:47]
	v_mfma_f32_16x16x32_bf16 v[16:19], v[144:147], v[16:19], v[40:43]
	v_mfma_f32_16x16x32_bf16 v[40:43], v[132:135], v[124:127], v[108:111]
	v_mfma_f32_16x16x32_bf16 v[44:47], v[136:139], v[124:127], v[116:119]
	v_mfma_f32_16x16x32_bf16 v[48:51], v[140:143], v[124:127], v[120:123]
	v_mfma_f32_16x16x32_bf16 v[72:75], v[144:147], v[124:127], v[112:115]
	s_waitcnt vmcnt(6)
	ds_write_b128 v103, v[12:15] offset:53248
	ds_write_b128 v103, v[20:23] offset:49152
	ds_write_b128 v103, v[24:27] offset:45056
	ds_write_b128 v103, v[36:39] offset:32768
	ds_write_b128 v103, v[32:35] offset:36864
	ds_write_b128 v103, v[28:31] offset:40960
	s_waitcnt lgkmcnt(0)
	s_barrier
	s_min_u32 s3, s2, 12
	s_lshl_b32 s92, s3, 7
	v_lshl_add_u64 v[12:13], v[80:81], 0, s[92:93]
	v_add_co_u32_e32 v14, vcc, s11, v12
	s_nop 1
	v_addc_co_u32_e32 v15, vcc, 0, v13, vcc
	global_load_dwordx4 v[36:39], v[12:13], off offset:384
	global_load_dwordx4 v[32:35], v[14:15], off offset:384
	v_add_co_u32_e32 v14, vcc, s33, v12
	s_nop 1
	v_addc_co_u32_e32 v15, vcc, 0, v13, vcc
	v_add_co_u32_e32 v12, vcc, s59, v12
	global_load_dwordx4 v[28:31], v[14:15], off offset:384
	s_nop 1
	v_addc_co_u32_e32 v13, vcc, 0, v13, vcc
	global_load_dwordx4 v[24:27], v[12:13], off offset:384
	v_lshl_add_u64 v[12:13], v[82:83], 0, s[92:93]
	global_load_dwordx4 v[20:23], v[12:13], off offset:384
	v_add_co_u32_e32 v12, vcc, s11, v12
	s_nop 1
	v_addc_co_u32_e32 v13, vcc, 0, v13, vcc
	global_load_dwordx4 v[12:15], v[12:13], off offset:384
	ds_read_b128 v[116:119], v130 offset:49152
	ds_read_b128 v[120:123], v130 offset:51200
	ds_read_b128 v[124:127], v130 offset:53248
	ds_read_b128 v[132:135], v130 offset:55296
	ds_read_b128 v[108:111], v128 offset:32768
	ds_read_b128 v[112:115], v128 offset:34816
	ds_read_b128 v[136:139], v149 offset:51200
	ds_read_b128 v[140:143], v149 offset:53248
	ds_read_b128 v[144:147], v149 offset:55296
	s_waitcnt lgkmcnt(4)
	v_mfma_f32_16x16x32_bf16 v[0:3], v[116:119], v[108:111], v[0:3]
	v_mfma_f32_16x16x32_bf16 v[4:7], v[120:123], v[108:111], v[4:7]
	v_mfma_f32_16x16x32_bf16 v[8:11], v[124:127], v[108:111], v[8:11]
	v_mfma_f32_16x16x32_bf16 v[16:19], v[132:135], v[108:111], v[16:19]
	s_waitcnt lgkmcnt(3)
	v_mfma_f32_16x16x32_bf16 v[108:111], v[116:119], v[112:115], v[40:43]
	s_nop 2
	ds_read_b128 v[40:43], v148 offset:32768
	v_mfma_f32_16x16x32_bf16 v[116:119], v[120:123], v[112:115], v[44:47]
	v_mfma_f32_16x16x32_bf16 v[120:123], v[124:127], v[112:115], v[48:51]
	ds_read_b128 v[124:127], v148 offset:34816
	v_mfma_f32_16x16x32_bf16 v[112:115], v[132:135], v[112:115], v[72:75]
	ds_read_b128 v[132:135], v149 offset:49152
	s_waitcnt lgkmcnt(0)
	v_mfma_f32_16x16x32_bf16 v[72:75], v[132:135], v[40:43], v[0:3]
	v_mfma_f32_16x16x32_bf16 v[48:51], v[136:139], v[40:43], v[4:7]
	v_mfma_f32_16x16x32_bf16 v[44:47], v[140:143], v[40:43], v[8:11]
	v_mfma_f32_16x16x32_bf16 v[40:43], v[144:147], v[40:43], v[16:19]
	v_mfma_f32_16x16x32_bf16 v[16:19], v[132:135], v[124:127], v[108:111]
	v_mfma_f32_16x16x32_bf16 v[8:11], v[136:139], v[124:127], v[116:119]
	v_mfma_f32_16x16x32_bf16 v[4:7], v[140:143], v[124:127], v[120:123]
	v_mfma_f32_16x16x32_bf16 v[0:3], v[144:147], v[124:127], v[112:115]
	s_waitcnt vmcnt(6)
	ds_write_b128 v103, v[52:55] offset:20480
	ds_write_b128 v103, v[56:59] offset:16384
	ds_write_b128 v103, v[60:63] offset:12288
	ds_write_b128 v103, v[76:79]
	ds_write_b128 v103, v[68:71] offset:4096
	ds_write_b128 v103, v[64:67] offset:8192
	s_cmp_lt_u32 s2, 12
	s_mov_b32 s3, s2
	s_waitcnt lgkmcnt(0)
	s_barrier
	s_cbranch_scc1 .LBB0_739
.Ltail739:
	s_add_i32 s2, s3, 2
	s_add_i32 s3, s3, 4
	s_min_u32 s3, s3, 15
	s_lshl_b32 s92, s3, 7
	v_add_u32_e32 v130, v105, v106
	ds_read_b128 v[116:119], v130 offset:16384
	ds_read_b128 v[120:123], v130 offset:18432
	ds_read_b128 v[124:127], v130 offset:20480
	ds_read_b128 v[132:135], v130 offset:22528
	v_add_u32_e32 v128, v104, v106
	ds_read_b128 v[108:111], v128
	ds_read_b128 v[112:115], v128 offset:2048
	v_add_u32_e32 v148, v104, v107
	v_add_u32_e32 v149, v105, v107
	ds_read_b128 v[136:139], v149 offset:18432
	ds_read_b128 v[140:143], v149 offset:20480
	ds_read_b128 v[144:147], v149 offset:22528
	s_waitcnt lgkmcnt(4)
	v_mfma_f32_16x16x32_bf16 v[72:75], v[116:119], v[108:111], v[72:75]
	v_mfma_f32_16x16x32_bf16 v[48:51], v[120:123], v[108:111], v[48:51]
	v_mfma_f32_16x16x32_bf16 v[44:47], v[124:127], v[108:111], v[44:47]
	v_mfma_f32_16x16x32_bf16 v[40:43], v[132:135], v[108:111], v[40:43]
	s_waitcnt lgkmcnt(3)
	v_mfma_f32_16x16x32_bf16 v[108:111], v[116:119], v[112:115], v[16:19]
	s_nop 2
	ds_read_b128 v[16:19], v148
	v_mfma_f32_16x16x32_bf16 v[116:119], v[120:123], v[112:115], v[8:11]
	v_mfma_f32_16x16x32_bf16 v[120:123], v[124:127], v[112:115], v[4:7]
	ds_read_b128 v[124:127], v148 offset:2048
	v_mfma_f32_16x16x32_bf16 v[112:115], v[132:135], v[112:115], v[0:3]
	ds_read_b128 v[132:135], v149 offset:16384
	s_waitcnt lgkmcnt(0)
	v_mfma_f32_16x16x32_bf16 v[0:3], v[132:135], v[16:19], v[72:75]
	v_mfma_f32_16x16x32_bf16 v[4:7], v[136:139], v[16:19], v[48:51]
	v_mfma_f32_16x16x32_bf16 v[8:11], v[140:143], v[16:19], v[44:47]
	v_mfma_f32_16x16x32_bf16 v[16:19], v[144:147], v[16:19], v[40:43]
	v_mfma_f32_16x16x32_bf16 v[40:43], v[132:135], v[124:127], v[108:111]
	v_mfma_f32_16x16x32_bf16 v[44:47], v[136:139], v[124:127], v[116:119]
	v_mfma_f32_16x16x32_bf16 v[48:51], v[140:143], v[124:127], v[120:123]
	v_mfma_f32_16x16x32_bf16 v[72:75], v[144:147], v[124:127], v[112:115]
	s_waitcnt vmcnt(0)
	ds_write_b128 v103, v[12:15] offset:53248
	s_waitcnt vmcnt(1)
	ds_write_b128 v103, v[20:23] offset:49152
	s_waitcnt vmcnt(2)
	ds_write_b128 v103, v[24:27] offset:45056
	s_waitcnt vmcnt(5)
	ds_write_b128 v103, v[36:39] offset:32768
	s_waitcnt vmcnt(4)
	ds_write_b128 v103, v[32:35] offset:36864
	s_waitcnt vmcnt(3)
	ds_write_b128 v103, v[28:31] offset:40960
	s_waitcnt lgkmcnt(0)
	s_barrier
	s_min_u32 s3, s2, 12
	s_lshl_b32 s92, s3, 7
	ds_read_b128 v[116:119], v130 offset:49152
	ds_read_b128 v[120:123], v130 offset:51200
	ds_read_b128 v[124:127], v130 offset:53248
	ds_read_b128 v[132:135], v130 offset:55296
	ds_read_b128 v[108:111], v128 offset:32768
	ds_read_b128 v[112:115], v128 offset:34816
	ds_read_b128 v[136:139], v149 offset:51200
	ds_read_b128 v[140:143], v149 offset:53248
	ds_read_b128 v[144:147], v149 offset:55296
	s_waitcnt lgkmcnt(4)
	v_mfma_f32_16x16x32_bf16 v[0:3], v[116:119], v[108:111], v[0:3]
	v_mfma_f32_16x16x32_bf16 v[4:7], v[120:123], v[108:111], v[4:7]
	v_mfma_f32_16x16x32_bf16 v[8:11], v[124:127], v[108:111], v[8:11]
	v_mfma_f32_16x16x32_bf16 v[16:19], v[132:135], v[108:111], v[16:19]
	s_waitcnt lgkmcnt(3)
	v_mfma_f32_16x16x32_bf16 v[108:111], v[116:119], v[112:115], v[40:43]
	s_nop 2
	ds_read_b128 v[40:43], v148 offset:32768
	v_mfma_f32_16x16x32_bf16 v[116:119], v[120:123], v[112:115], v[44:47]
	v_mfma_f32_16x16x32_bf16 v[120:123], v[124:127], v[112:115], v[48:51]
	ds_read_b128 v[124:127], v148 offset:34816
	v_mfma_f32_16x16x32_bf16 v[112:115], v[132:135], v[112:115], v[72:75]
	ds_read_b128 v[132:135], v149 offset:49152
	s_waitcnt lgkmcnt(0)
	v_mfma_f32_16x16x32_bf16 v[72:75], v[132:135], v[40:43], v[0:3]
	v_mfma_f32_16x16x32_bf16 v[48:51], v[136:139], v[40:43], v[4:7]
	v_mfma_f32_16x16x32_bf16 v[44:47], v[140:143], v[40:43], v[8:11]
	v_mfma_f32_16x16x32_bf16 v[40:43], v[144:147], v[40:43], v[16:19]
	v_mfma_f32_16x16x32_bf16 v[16:19], v[132:135], v[124:127], v[108:111]
	v_mfma_f32_16x16x32_bf16 v[8:11], v[136:139], v[124:127], v[116:119]
	v_mfma_f32_16x16x32_bf16 v[4:7], v[140:143], v[124:127], v[120:123]
	v_mfma_f32_16x16x32_bf16 v[0:3], v[144:147], v[124:127], v[112:115]
	s_mov_b32 s3, s2
	s_waitcnt lgkmcnt(0)
	s_barrier
	s_movk_i32 s2, 0x80
	v_cmp_gt_i32_e32 vcc, s2, v85
	s_and_saveexec_b64 s[2:3], vcc
	s_cbranch_execz .LBB0_742
	s_waitcnt vmcnt(0)
	v_add_f32_e32 v12, 0, v102
	v_add_f32_e32 v12, v12, v86
	v_add_f32_e32 v12, v12, v87
	v_add_f32_e32 v12, v12, v88
	v_add_f32_e32 v12, v12, v89
	v_add_f32_e32 v12, v12, v90
	v_add_f32_e32 v12, v12, v91
	v_add_f32_e32 v12, v12, v92
	v_add_f32_e32 v12, v12, v93
	v_add_f32_e32 v12, v12, v95
	v_add_f32_e32 v12, v12, v96
	v_add_f32_e32 v12, v12, v97
	v_add_f32_e32 v12, v12, v98
	v_add_f32_e32 v12, v12, v99
	v_add_f32_e32 v12, v12, v100
	v_add_f32_e32 v12, v12, v101
	v_fmamk_f32 v12, v12, 0x3a800000, v167
	s_mov_b32 s16, 0x800000
	v_mul_f32_e32 v13, 0x4b800000, v12
	v_cmp_gt_f32_e32 vcc, s16, v12
	s_nop 1
	v_cndmask_b32_e32 v12, v12, v13, vcc
	v_rsq_f32_e32 v12, v12
	v_lshl_add_u32 v13, v85, 2, 0
	v_add_u32_e32 v13, 0x10000, v13
	v_mul_f32_e32 v14, 0x45800000, v12
	v_cndmask_b32_e32 v12, v12, v14, vcc
	ds_write_b32 v13, v12
